# v53 + EpiRes epilogues (P3/P5/P8/P10): rms partial xor-16/xor-32 reduction via permlane16/32 swaps instead of two serialized ds_bpermute round trips per row group
# baseline (speedup 1.0000x reference)
.LBB0_404:
	v_lshl_or_b32 v168, s10, 8, v188
	v_lshl_add_u32 v172, s40, 8, v186
	v_ashrrev_i32_e32 v169, 31, v168
	v_lshlrev_b64 v[204:205], 1, v[168:169]
	v_ashrrev_i32_e32 v173, 31, v172
	v_lshl_add_u64 v[170:171], s[16:17], 0, v[204:205]
	v_lshlrev_b64 v[206:207], 11, v[172:173]
	v_lshl_add_u64 v[128:129], v[170:171], 0, v[206:207]
	global_load_dwordx4 v[194:197], v[128:129], off
	global_load_dwordx4 v[198:201], v[128:129], off offset:256
	v_or_b32_e32 v182, 16, v172
	v_or_b32_e32 v178, 32, v172
	v_or_b32_e32 v174, 48, v172
	v_ashrrev_i32_e32 v183, 31, v182
	v_ashrrev_i32_e32 v179, 31, v178
	v_ashrrev_i32_e32 v175, 31, v174
	v_lshlrev_b64 v[184:185], 11, v[182:183]
	v_lshlrev_b64 v[180:181], 11, v[178:179]
	v_lshlrev_b64 v[176:177], 11, v[174:175]
	v_lshl_add_u64 v[128:129], v[170:171], 0, v[184:185]
	v_lshl_add_u64 v[130:131], v[170:171], 0, v[180:181]
	v_lshl_add_u64 v[208:209], v[170:171], 0, v[176:177]
	global_load_dwordx4 v[148:151], v[128:129], off
	global_load_dwordx4 v[144:147], v[128:129], off offset:256
	global_load_dwordx4 v[140:143], v[130:131], off
	global_load_dwordx4 v[136:139], v[130:131], off offset:256
	global_load_dwordx4 v[132:135], v[208:209], off
	s_nop 0
	global_load_dwordx4 v[128:131], v[208:209], off offset:256
	v_add_u32_e32 v248, 0x80, v172
	v_ashrrev_i32_e32 v249, 31, v248
	v_lshlrev_b64 v[248:249], 11, v[248:249]
	v_lshl_add_u64 v[248:249], v[170:171], 0, v[248:249]
	global_load_dwordx4 v[216:219], v[248:249], off
	global_load_dwordx4 v[220:223], v[248:249], off offset:256
	v_add_u32_e32 v250, 0x90, v172
	v_ashrrev_i32_e32 v251, 31, v250
	v_lshlrev_b64 v[250:251], 11, v[250:251]
	v_lshl_add_u64 v[250:251], v[170:171], 0, v[250:251]
	global_load_dwordx4 v[224:227], v[250:251], off
	global_load_dwordx4 v[228:231], v[250:251], off offset:256
	v_add_u32_e32 v252, 0xa0, v172
	v_ashrrev_i32_e32 v253, 31, v252
	v_lshlrev_b64 v[252:253], 11, v[252:253]
	v_lshl_add_u64 v[252:253], v[170:171], 0, v[252:253]
	global_load_dwordx4 v[232:235], v[252:253], off
	global_load_dwordx4 v[236:239], v[252:253], off offset:256
	v_add_u32_e32 v248, 0xb0, v172
	v_ashrrev_i32_e32 v249, 31, v248
	v_lshlrev_b64 v[248:249], 11, v[248:249]
	v_lshl_add_u64 v[248:249], v[170:171], 0, v[248:249]
	global_load_dwordx4 v[240:243], v[248:249], off
	global_load_dwordx4 v[244:247], v[248:249], off offset:256
	v_and_b32_e32 v208, 64, v192
	v_xor_b32_e32 v193, 16, v192
	v_add_u32_e32 v208, 64, v208
	v_xor_b32_e32 v209, 32, v192
	v_cmp_lt_i32_e32 vcc, v193, v208
	v_lshl_add_u64 v[206:207], s[16:17], 0, v[206:207]
	v_lshl_add_u64 v[204:205], v[206:207], 0, v[204:205]
	v_cndmask_b32_e32 v193, v192, v193, vcc
	v_cmp_lt_i32_e32 vcc, v209, v208
	v_lshlrev_b32_e32 v193, 2, v193
	s_lshl_b32 s40, s10, 2
	v_cndmask_b32_e32 v214, v192, v209, vcc
	s_ashr_i32 s41, s40, 31
	s_waitcnt vmcnt(8)
	v_lshlrev_b32_e32 v206, 16, v194
	v_and_b32_e32 v207, 0xffff0000, v194
	v_lshlrev_b32_e32 v194, 16, v195
	v_and_b32_e32 v195, 0xffff0000, v195
	v_lshlrev_b32_e32 v208, 16, v196
	v_and_b32_e32 v209, 0xffff0000, v196
	v_lshlrev_b32_e32 v196, 16, v197
	v_and_b32_e32 v197, 0xffff0000, v197
	v_lshlrev_b32_e32 v210, 16, v198
	v_and_b32_e32 v211, 0xffff0000, v198
	v_lshlrev_b32_e32 v198, 16, v199
	v_and_b32_e32 v199, 0xffff0000, v199
	v_lshlrev_b32_e32 v212, 16, v200
	v_and_b32_e32 v213, 0xffff0000, v200
	v_lshlrev_b32_e32 v200, 16, v201
	v_and_b32_e32 v201, 0xffff0000, v201
	v_pk_add_f32 v[126:127], v[126:127], v[194:195]
	v_pk_add_f32 v[124:125], v[124:125], v[206:207]
	v_pk_add_f32 v[122:123], v[122:123], v[196:197]
	v_pk_add_f32 v[120:121], v[120:121], v[208:209]
	v_pk_add_f32 v[118:119], v[118:119], v[198:199]
	v_pk_add_f32 v[116:117], v[116:117], v[210:211]
	v_pk_add_f32 v[194:195], v[114:115], v[200:201]
	v_pk_add_f32 v[196:197], v[112:113], v[212:213]
	v_mul_f32_e32 v114, v125, v125
	v_mul_f32_e32 v115, v127, v127
	v_mul_f32_e32 v198, v121, v121
	v_mul_f32_e32 v199, v123, v123
	v_cvt_pk_bf16_f32 v112, v124, v125
	v_cvt_pk_bf16_f32 v113, v126, v127
	v_mul_f32_e32 v125, v117, v117
	v_mul_f32_e32 v127, v119, v119
	v_mul_f32_e32 v200, v197, v197
	v_mul_f32_e32 v201, v195, v195
	v_fmac_f32_e32 v114, v124, v124
	v_fmac_f32_e32 v115, v126, v126
	v_fmac_f32_e32 v198, v120, v120
	v_fmac_f32_e32 v199, v122, v122
	v_fmac_f32_e32 v125, v116, v116
	v_fmac_f32_e32 v127, v118, v118
	v_fmac_f32_e32 v200, v196, v196
	v_fmac_f32_e32 v201, v194, v194
	v_add_f32_e32 v114, v114, v115
	v_add_f32_e32 v115, v198, v199
	v_add_f32_e32 v124, v125, v127
	v_add_f32_e32 v125, v200, v201
	v_add_f32_e32 v114, v114, v115
	v_add_f32_e32 v115, v124, v125
	v_add_f32_e32 v124, v114, v115
	v_mov_b32_e32 v125, v124
	v_cvt_pk_bf16_f32 v114, v120, v121
	v_cvt_pk_bf16_f32 v115, v122, v123
	global_store_dwordx4 v[204:205], v[112:115], off
	v_cvt_pk_bf16_f32 v116, v116, v117
	v_cvt_pk_bf16_f32 v117, v118, v119
	v_cvt_pk_bf16_f32 v118, v196, v197
	v_cvt_pk_bf16_f32 v119, v194, v195
	global_store_dwordx4 v[204:205], v[116:119], off offset:256
	s_waitcnt lgkmcnt(0)
	v_permlane16_swap_b32_e32 v124, v125
	v_add_f32_e32 v113, v124, v125
	v_lshlrev_b32_e32 v112, 2, v214
	v_mov_b32_e32 v114, v113
	s_nop 1
	v_permlane32_swap_b32_e32 v113, v114
	v_add_f32_e32 v113, v113, v114
	s_and_saveexec_b64 s[4:5], s[6:7]
	s_cbranch_execz .LBB0_406
	v_lshlrev_b64 v[116:117], 6, v[172:173]
	v_lshl_add_u64 v[116:117], s[22:23], 0, v[116:117]
	v_lshl_add_u64 v[116:117], s[40:41], 2, v[116:117]
	s_lshl_b32 s10, s51, 2
	v_lshl_add_u64 v[116:117], v[116:117], 0, s[10:11]
	global_store_dword v[116:117], v113, off
.LBB0_406:
	s_or_b64 exec, exec, s[4:5]
	s_waitcnt lgkmcnt(0)
	v_lshlrev_b32_e32 v114, 16, v148
	v_and_b32_e32 v115, 0xffff0000, v148
	v_lshlrev_b32_e32 v116, 16, v149
	v_and_b32_e32 v117, 0xffff0000, v149
	v_lshlrev_b32_e32 v118, 16, v150
	v_and_b32_e32 v119, 0xffff0000, v150
	v_lshlrev_b32_e32 v120, 16, v151
	v_and_b32_e32 v121, 0xffff0000, v151
	v_pk_add_f32 v[110:111], v[110:111], v[116:117]
	v_pk_add_f32 v[108:109], v[108:109], v[114:115]
	v_pk_add_f32 v[114:115], v[106:107], v[120:121]
	v_pk_add_f32 v[106:107], v[104:105], v[118:119]
	v_mul_f32_e32 v104, v109, v109
	v_mul_f32_e32 v105, v111, v111
	v_fmac_f32_e32 v104, v108, v108
	v_fmac_f32_e32 v105, v110, v110
	v_add_f32_e32 v104, v104, v105
	v_mul_f32_e32 v105, v107, v107
	v_mul_f32_e32 v113, v115, v115
	v_fmac_f32_e32 v105, v106, v106
	v_fmac_f32_e32 v113, v114, v114
	v_add_f32_e32 v105, v105, v113
	v_add_f32_e32 v113, v104, v105
	v_cvt_pk_bf16_f32 v104, v108, v109
	v_cvt_pk_bf16_f32 v105, v110, v111
	v_lshlrev_b32_e32 v108, 16, v144
	v_and_b32_e32 v109, 0xffff0000, v144
	v_lshlrev_b32_e32 v110, 16, v145
	v_and_b32_e32 v111, 0xffff0000, v145
	v_cvt_pk_bf16_f32 v106, v106, v107
	v_cvt_pk_bf16_f32 v107, v114, v115
	v_lshlrev_b32_e32 v114, 16, v146
	v_and_b32_e32 v115, 0xffff0000, v146
	v_pk_add_f32 v[102:103], v[102:103], v[110:111]
	v_pk_add_f32 v[100:101], v[100:101], v[108:109]
	v_lshlrev_b32_e32 v116, 16, v147
	v_and_b32_e32 v117, 0xffff0000, v147
	v_pk_add_f32 v[110:111], v[96:97], v[114:115]
	v_mul_f32_e32 v96, v101, v101
	v_mul_f32_e32 v97, v103, v103
	v_pk_add_f32 v[108:109], v[98:99], v[116:117]
	v_fmac_f32_e32 v96, v100, v100
	v_fmac_f32_e32 v97, v102, v102
	v_add_f32_e32 v96, v96, v97
	v_mul_f32_e32 v97, v111, v111
	v_mul_f32_e32 v98, v109, v109
	v_fmac_f32_e32 v97, v110, v110
	v_fmac_f32_e32 v98, v108, v108
	v_add_f32_e32 v97, v97, v98
	v_add_f32_e32 v96, v96, v97
	v_add_f32_e32 v99, v113, v96
	v_mov_b32_e32 v113, v99
	v_lshl_add_u64 v[96:97], s[16:17], 0, v[184:185]
	v_lshl_add_u64 v[114:115], v[168:169], 1, v[96:97]
	global_store_dwordx4 v[114:115], v[104:107], off
	v_cvt_pk_bf16_f32 v98, v100, v101
	s_waitcnt lgkmcnt(0)
	v_permlane16_swap_b32_e32 v99, v113
	v_add_f32_e32 v96, v99, v113
	v_mov_b32_e32 v97, v96
	v_cvt_pk_bf16_f32 v99, v102, v103
	v_cvt_pk_bf16_f32 v100, v110, v111
	v_cvt_pk_bf16_f32 v101, v108, v109
	global_store_dwordx4 v[114:115], v[98:101], off offset:256
	v_permlane32_swap_b32_e32 v96, v97
	v_add_f32_e32 v96, v96, v97
	s_and_saveexec_b64 s[4:5], s[6:7]
	s_cbranch_execz .LBB0_408
	v_lshlrev_b64 v[98:99], 6, v[182:183]
	v_lshl_add_u64 v[98:99], s[22:23], 0, v[98:99]
	v_lshl_add_u64 v[98:99], s[40:41], 2, v[98:99]
	s_lshl_b32 s10, s51, 2
	v_lshl_add_u64 v[98:99], v[98:99], 0, s[10:11]
	global_store_dword v[98:99], v96, off
.LBB0_408:
	s_or_b64 exec, exec, s[4:5]
	v_lshlrev_b32_e32 v96, 16, v140
	s_waitcnt lgkmcnt(0)
	v_and_b32_e32 v97, 0xffff0000, v140
	v_lshlrev_b32_e32 v98, 16, v141
	v_and_b32_e32 v99, 0xffff0000, v141
	v_lshlrev_b32_e32 v100, 16, v142
	v_and_b32_e32 v101, 0xffff0000, v142
	v_lshlrev_b32_e32 v102, 16, v143
	v_and_b32_e32 v103, 0xffff0000, v143
	v_pk_add_f32 v[94:95], v[94:95], v[98:99]
	v_pk_add_f32 v[92:93], v[92:93], v[96:97]
	v_pk_add_f32 v[96:97], v[90:91], v[102:103]
	v_pk_add_f32 v[90:91], v[88:89], v[100:101]
	v_mul_f32_e32 v88, v93, v93
	v_mul_f32_e32 v89, v95, v95
	v_fmac_f32_e32 v88, v92, v92
	v_fmac_f32_e32 v89, v94, v94
	v_add_f32_e32 v88, v88, v89
	v_mul_f32_e32 v89, v91, v91
	v_mul_f32_e32 v98, v97, v97
	v_fmac_f32_e32 v89, v90, v90
	v_fmac_f32_e32 v98, v96, v96
	v_add_f32_e32 v89, v89, v98
	v_add_f32_e32 v100, v88, v89
	v_cvt_pk_bf16_f32 v88, v92, v93
	v_cvt_pk_bf16_f32 v89, v94, v95
	v_lshlrev_b32_e32 v92, 16, v136
	v_and_b32_e32 v93, 0xffff0000, v136
	v_lshlrev_b32_e32 v94, 16, v137
	v_and_b32_e32 v95, 0xffff0000, v137
	v_cvt_pk_bf16_f32 v90, v90, v91
	v_cvt_pk_bf16_f32 v91, v96, v97
	v_lshlrev_b32_e32 v96, 16, v138
	v_and_b32_e32 v97, 0xffff0000, v138
	v_pk_add_f32 v[86:87], v[86:87], v[94:95]
	v_pk_add_f32 v[84:85], v[84:85], v[92:93]
	v_lshlrev_b32_e32 v98, 16, v139
	v_and_b32_e32 v99, 0xffff0000, v139
	v_pk_add_f32 v[94:95], v[80:81], v[96:97]
	v_mul_f32_e32 v80, v85, v85
	v_mul_f32_e32 v81, v87, v87
	v_pk_add_f32 v[92:93], v[82:83], v[98:99]
	v_fmac_f32_e32 v80, v84, v84
	v_fmac_f32_e32 v81, v86, v86
	v_add_f32_e32 v80, v80, v81
	v_mul_f32_e32 v81, v95, v95
	v_mul_f32_e32 v82, v93, v93
	v_fmac_f32_e32 v81, v94, v94
	v_fmac_f32_e32 v82, v92, v92
	v_add_f32_e32 v81, v81, v82
	v_add_f32_e32 v80, v80, v81
	v_add_f32_e32 v83, v100, v80
	v_mov_b32_e32 v98, v83
	v_lshl_add_u64 v[80:81], s[16:17], 0, v[180:181]
	v_lshl_add_u64 v[96:97], v[168:169], 1, v[80:81]
	global_store_dwordx4 v[96:97], v[88:91], off
	v_cvt_pk_bf16_f32 v82, v84, v85
	s_waitcnt lgkmcnt(0)
	v_permlane16_swap_b32_e32 v83, v98
	v_add_f32_e32 v80, v83, v98
	v_mov_b32_e32 v81, v80
	v_cvt_pk_bf16_f32 v83, v86, v87
	v_cvt_pk_bf16_f32 v84, v94, v95
	v_cvt_pk_bf16_f32 v85, v92, v93
	global_store_dwordx4 v[96:97], v[82:85], off offset:256
	v_permlane32_swap_b32_e32 v80, v81
	v_add_f32_e32 v80, v80, v81
	s_and_saveexec_b64 s[4:5], s[6:7]
	s_cbranch_execz .LBB0_410
	v_lshlrev_b64 v[82:83], 6, v[178:179]
	v_lshl_add_u64 v[82:83], s[22:23], 0, v[82:83]
	v_lshl_add_u64 v[82:83], s[40:41], 2, v[82:83]
	s_lshl_b32 s10, s51, 2
	v_lshl_add_u64 v[82:83], v[82:83], 0, s[10:11]
	global_store_dword v[82:83], v80, off
.LBB0_410:
	s_or_b64 exec, exec, s[4:5]
	v_lshlrev_b32_e32 v80, 16, v132
	s_waitcnt lgkmcnt(0)
	v_and_b32_e32 v81, 0xffff0000, v132
	v_lshlrev_b32_e32 v82, 16, v133
	v_and_b32_e32 v83, 0xffff0000, v133
	v_lshlrev_b32_e32 v84, 16, v134
	v_and_b32_e32 v85, 0xffff0000, v134
	v_lshlrev_b32_e32 v86, 16, v135
	v_and_b32_e32 v87, 0xffff0000, v135
	v_pk_add_f32 v[78:79], v[78:79], v[82:83]
	v_pk_add_f32 v[76:77], v[76:77], v[80:81]
	v_pk_add_f32 v[80:81], v[74:75], v[86:87]
	v_pk_add_f32 v[74:75], v[72:73], v[84:85]
	v_mul_f32_e32 v72, v77, v77
	v_mul_f32_e32 v73, v79, v79
	v_fmac_f32_e32 v72, v76, v76
	v_fmac_f32_e32 v73, v78, v78
	v_add_f32_e32 v72, v72, v73
	v_mul_f32_e32 v73, v75, v75
	v_mul_f32_e32 v82, v81, v81
	v_fmac_f32_e32 v73, v74, v74
	v_fmac_f32_e32 v82, v80, v80
	v_add_f32_e32 v73, v73, v82
	v_add_f32_e32 v84, v72, v73
	v_cvt_pk_bf16_f32 v72, v76, v77
	v_cvt_pk_bf16_f32 v73, v78, v79
	v_lshlrev_b32_e32 v76, 16, v128
	v_and_b32_e32 v77, 0xffff0000, v128
	v_lshlrev_b32_e32 v78, 16, v129
	v_and_b32_e32 v79, 0xffff0000, v129
	v_cvt_pk_bf16_f32 v74, v74, v75
	v_cvt_pk_bf16_f32 v75, v80, v81
	v_lshlrev_b32_e32 v80, 16, v130
	v_and_b32_e32 v81, 0xffff0000, v130
	v_pk_add_f32 v[70:71], v[70:71], v[78:79]
	v_pk_add_f32 v[68:69], v[68:69], v[76:77]
	v_lshlrev_b32_e32 v82, 16, v131
	v_and_b32_e32 v83, 0xffff0000, v131
	v_pk_add_f32 v[78:79], v[64:65], v[80:81]
	v_mul_f32_e32 v64, v69, v69
	v_mul_f32_e32 v65, v71, v71
	v_pk_add_f32 v[76:77], v[66:67], v[82:83]
	v_fmac_f32_e32 v64, v68, v68
	v_fmac_f32_e32 v65, v70, v70
	v_add_f32_e32 v64, v64, v65
	v_mul_f32_e32 v65, v79, v79
	v_mul_f32_e32 v66, v77, v77
	v_fmac_f32_e32 v65, v78, v78
	v_fmac_f32_e32 v66, v76, v76
	v_add_f32_e32 v65, v65, v66
	v_add_f32_e32 v64, v64, v65
	v_add_f32_e32 v67, v84, v64
	v_mov_b32_e32 v82, v67
	v_lshl_add_u64 v[64:65], s[16:17], 0, v[176:177]
	v_lshl_add_u64 v[80:81], v[168:169], 1, v[64:65]
	global_store_dwordx4 v[80:81], v[72:75], off
	v_cvt_pk_bf16_f32 v66, v68, v69
	s_waitcnt lgkmcnt(0)
	v_permlane16_swap_b32_e32 v67, v82
	v_add_f32_e32 v64, v67, v82
	v_mov_b32_e32 v65, v64
	v_cvt_pk_bf16_f32 v67, v70, v71
	v_cvt_pk_bf16_f32 v68, v78, v79
	v_cvt_pk_bf16_f32 v69, v76, v77
	global_store_dwordx4 v[80:81], v[66:69], off offset:256
	v_permlane32_swap_b32_e32 v64, v65
	v_add_f32_e32 v64, v64, v65
	s_and_saveexec_b64 s[4:5], s[6:7]
	s_cbranch_execz .LBB0_412
	v_lshlrev_b64 v[66:67], 6, v[174:175]
	v_lshl_add_u64 v[66:67], s[22:23], 0, v[66:67]
	v_lshl_add_u64 v[66:67], s[40:41], 2, v[66:67]
	s_lshl_b32 s10, s51, 2
	v_lshl_add_u64 v[66:67], v[66:67], 0, s[10:11]
	global_store_dword v[66:67], v64, off
.LBB0_412:
	s_or_b64 exec, exec, s[4:5]
	v_add_u32_e32 v100, 0x80, v172
	v_ashrrev_i32_e32 v101, 31, v100
	v_lshlrev_b64 v[110:111], 11, v[100:101]
	s_waitcnt lgkmcnt(0)
	v_lshl_add_u64 v[64:65], v[170:171], 0, v[110:111]
	v_add_u32_e32 v96, 0x90, v172
	v_add_u32_e32 v92, 0xa0, v172
	v_add_u32_e32 v88, 0xb0, v172
	v_ashrrev_i32_e32 v97, 31, v96
	v_ashrrev_i32_e32 v93, 31, v92
	v_ashrrev_i32_e32 v89, 31, v88
	v_lshlrev_b64 v[98:99], 11, v[96:97]
	v_lshlrev_b64 v[94:95], 11, v[92:93]
	v_lshlrev_b64 v[90:91], 11, v[88:89]
	v_lshl_add_u64 v[64:65], v[170:171], 0, v[98:99]
	v_lshl_add_u64 v[66:67], v[170:171], 0, v[94:95]
	v_lshl_add_u64 v[114:115], v[170:171], 0, v[90:91]
	s_waitcnt vmcnt(15)
	v_lshlrev_b32_e32 v114, 16, v216
	v_and_b32_e32 v115, 0xffff0000, v216
	v_lshlrev_b32_e32 v102, 16, v217
	v_and_b32_e32 v103, 0xffff0000, v217
	v_lshlrev_b32_e32 v116, 16, v218
	v_and_b32_e32 v117, 0xffff0000, v218
	v_lshlrev_b32_e32 v104, 16, v219
	v_and_b32_e32 v105, 0xffff0000, v219
	s_waitcnt vmcnt(14)
	v_lshlrev_b32_e32 v118, 16, v220
	v_and_b32_e32 v119, 0xffff0000, v220
	v_lshlrev_b32_e32 v106, 16, v221
	v_and_b32_e32 v107, 0xffff0000, v221
	v_lshlrev_b32_e32 v120, 16, v222
	v_and_b32_e32 v121, 0xffff0000, v222
	v_lshlrev_b32_e32 v108, 16, v223
	v_and_b32_e32 v109, 0xffff0000, v223
	v_pk_add_f32 v[62:63], v[62:63], v[102:103]
	v_pk_add_f32 v[60:61], v[60:61], v[114:115]
	v_pk_add_f32 v[58:59], v[58:59], v[104:105]
	v_pk_add_f32 v[56:57], v[56:57], v[116:117]
	v_pk_add_f32 v[54:55], v[54:55], v[106:107]
	v_pk_add_f32 v[52:53], v[52:53], v[118:119]
	v_pk_add_f32 v[102:103], v[50:51], v[108:109]
	v_pk_add_f32 v[104:105], v[48:49], v[120:121]
	v_mul_f32_e32 v106, v61, v61
	v_mul_f32_e32 v107, v63, v63
	v_mul_f32_e32 v108, v57, v57
	v_mul_f32_e32 v109, v59, v59
	v_cvt_pk_bf16_f32 v48, v60, v61
	v_cvt_pk_bf16_f32 v49, v62, v63
	v_cvt_pk_bf16_f32 v50, v56, v57
	v_cvt_pk_bf16_f32 v51, v58, v59
	v_mul_f32_e32 v57, v53, v53
	v_mul_f32_e32 v59, v55, v55
	v_mul_f32_e32 v61, v105, v105
	v_mul_f32_e32 v63, v103, v103
	v_fmac_f32_e32 v106, v60, v60
	v_fmac_f32_e32 v107, v62, v62
	v_fmac_f32_e32 v108, v56, v56
	v_fmac_f32_e32 v109, v58, v58
	v_fmac_f32_e32 v57, v52, v52
	v_fmac_f32_e32 v59, v54, v54
	v_fmac_f32_e32 v61, v104, v104
	v_fmac_f32_e32 v63, v102, v102
	v_add_f32_e32 v56, v106, v107
	v_add_f32_e32 v58, v108, v109
	v_add_f32_e32 v57, v57, v59
	v_add_f32_e32 v59, v61, v63
	v_add_f32_e32 v56, v56, v58
	v_add_f32_e32 v57, v57, v59
	v_add_f32_e32 v58, v56, v57
	v_mov_b32_e32 v59, v58
	v_lshl_add_u64 v[56:57], s[16:17], 0, v[110:111]
	v_lshl_add_u64 v[56:57], v[168:169], 1, v[56:57]
	global_store_dwordx4 v[56:57], v[48:51], off
	s_waitcnt lgkmcnt(0)
	s_nop 0
	v_permlane16_swap_b32_e32 v58, v59
	v_add_f32_e32 v48, v58, v59
	v_mov_b32_e32 v49, v48
	v_cvt_pk_bf16_f32 v50, v52, v53
	v_cvt_pk_bf16_f32 v51, v54, v55
	v_cvt_pk_bf16_f32 v52, v104, v105
	v_cvt_pk_bf16_f32 v53, v102, v103
	global_store_dwordx4 v[56:57], v[50:53], off offset:256
	v_permlane32_swap_b32_e32 v48, v49
	v_add_f32_e32 v48, v48, v49
	s_and_saveexec_b64 s[4:5], s[6:7]
	s_cbranch_execz .LBB0_414
	v_lshlrev_b64 v[50:51], 6, v[100:101]
	v_lshl_add_u64 v[50:51], s[22:23], 0, v[50:51]
	v_lshl_add_u64 v[50:51], s[40:41], 2, v[50:51]
	s_lshl_b32 s10, s51, 2
	v_lshl_add_u64 v[50:51], v[50:51], 0, s[10:11]
	global_store_dword v[50:51], v48, off
.LBB0_414:
	s_or_b64 exec, exec, s[4:5]
	s_waitcnt vmcnt(15)
	v_lshlrev_b32_e32 v48, 16, v224
	s_waitcnt lgkmcnt(0)
	v_and_b32_e32 v49, 0xffff0000, v224
	v_lshlrev_b32_e32 v50, 16, v225
	v_and_b32_e32 v51, 0xffff0000, v225
	v_lshlrev_b32_e32 v52, 16, v226
	v_and_b32_e32 v53, 0xffff0000, v226
	v_lshlrev_b32_e32 v54, 16, v227
	v_and_b32_e32 v55, 0xffff0000, v227
	v_pk_add_f32 v[46:47], v[46:47], v[50:51]
	v_pk_add_f32 v[44:45], v[44:45], v[48:49]
	v_pk_add_f32 v[48:49], v[42:43], v[54:55]
	v_pk_add_f32 v[42:43], v[40:41], v[52:53]
	v_mul_f32_e32 v40, v45, v45
	v_mul_f32_e32 v41, v47, v47
	v_fmac_f32_e32 v40, v44, v44
	v_fmac_f32_e32 v41, v46, v46
	v_add_f32_e32 v40, v40, v41
	v_mul_f32_e32 v41, v43, v43
	v_mul_f32_e32 v50, v49, v49
	v_fmac_f32_e32 v41, v42, v42
	v_fmac_f32_e32 v50, v48, v48
	v_add_f32_e32 v41, v41, v50
	v_add_f32_e32 v52, v40, v41
	v_cvt_pk_bf16_f32 v40, v44, v45
	v_cvt_pk_bf16_f32 v41, v46, v47
	s_waitcnt vmcnt(14)
	v_lshlrev_b32_e32 v44, 16, v228
	v_and_b32_e32 v45, 0xffff0000, v228
	v_lshlrev_b32_e32 v46, 16, v229
	v_and_b32_e32 v47, 0xffff0000, v229
	v_cvt_pk_bf16_f32 v42, v42, v43
	v_cvt_pk_bf16_f32 v43, v48, v49
	v_lshlrev_b32_e32 v48, 16, v230
	v_and_b32_e32 v49, 0xffff0000, v230
	v_pk_add_f32 v[38:39], v[38:39], v[46:47]
	v_pk_add_f32 v[36:37], v[36:37], v[44:45]
	v_lshlrev_b32_e32 v50, 16, v231
	v_and_b32_e32 v51, 0xffff0000, v231
	v_pk_add_f32 v[46:47], v[32:33], v[48:49]
	v_mul_f32_e32 v32, v37, v37
	v_mul_f32_e32 v33, v39, v39
	v_pk_add_f32 v[44:45], v[34:35], v[50:51]
	v_fmac_f32_e32 v32, v36, v36
	v_fmac_f32_e32 v33, v38, v38
	v_add_f32_e32 v32, v32, v33
	v_mul_f32_e32 v33, v47, v47
	v_mul_f32_e32 v34, v45, v45
	v_fmac_f32_e32 v33, v46, v46
	v_fmac_f32_e32 v34, v44, v44
	v_add_f32_e32 v33, v33, v34
	v_add_f32_e32 v32, v32, v33
	v_add_f32_e32 v35, v52, v32
	v_mov_b32_e32 v50, v35
	v_lshl_add_u64 v[32:33], s[16:17], 0, v[98:99]
	v_lshl_add_u64 v[48:49], v[168:169], 1, v[32:33]
	global_store_dwordx4 v[48:49], v[40:43], off
	v_cvt_pk_bf16_f32 v34, v36, v37
	s_waitcnt lgkmcnt(0)
	v_permlane16_swap_b32_e32 v35, v50
	v_add_f32_e32 v32, v35, v50
	v_mov_b32_e32 v33, v32
	v_cvt_pk_bf16_f32 v35, v38, v39
	v_cvt_pk_bf16_f32 v36, v46, v47
	v_cvt_pk_bf16_f32 v37, v44, v45
	global_store_dwordx4 v[48:49], v[34:37], off offset:256
	v_permlane32_swap_b32_e32 v32, v33
	v_add_f32_e32 v32, v32, v33
	s_and_saveexec_b64 s[4:5], s[6:7]
	s_cbranch_execz .LBB0_416
	v_lshlrev_b64 v[34:35], 6, v[96:97]
	v_lshl_add_u64 v[34:35], s[22:23], 0, v[34:35]
	v_lshl_add_u64 v[34:35], s[40:41], 2, v[34:35]
	s_lshl_b32 s10, s51, 2
	v_lshl_add_u64 v[34:35], v[34:35], 0, s[10:11]
	global_store_dword v[34:35], v32, off
.LBB0_416:
	s_or_b64 exec, exec, s[4:5]
	s_waitcnt vmcnt(15)
	v_lshlrev_b32_e32 v32, 16, v232
	s_waitcnt lgkmcnt(0)
	v_and_b32_e32 v33, 0xffff0000, v232
	v_lshlrev_b32_e32 v34, 16, v233
	v_and_b32_e32 v35, 0xffff0000, v233
	v_lshlrev_b32_e32 v36, 16, v234
	v_and_b32_e32 v37, 0xffff0000, v234
	v_lshlrev_b32_e32 v38, 16, v235
	v_and_b32_e32 v39, 0xffff0000, v235
	v_pk_add_f32 v[30:31], v[30:31], v[34:35]
	v_pk_add_f32 v[28:29], v[28:29], v[32:33]
	v_pk_add_f32 v[32:33], v[26:27], v[38:39]
	v_pk_add_f32 v[26:27], v[24:25], v[36:37]
	v_mul_f32_e32 v24, v29, v29
	v_mul_f32_e32 v25, v31, v31
	v_fmac_f32_e32 v24, v28, v28
	v_fmac_f32_e32 v25, v30, v30
	v_add_f32_e32 v24, v24, v25
	v_mul_f32_e32 v25, v27, v27
	v_mul_f32_e32 v34, v33, v33
	v_fmac_f32_e32 v25, v26, v26
	v_fmac_f32_e32 v34, v32, v32
	v_add_f32_e32 v25, v25, v34
	v_add_f32_e32 v36, v24, v25
	v_cvt_pk_bf16_f32 v24, v28, v29
	v_cvt_pk_bf16_f32 v25, v30, v31
	s_waitcnt vmcnt(14)
	v_lshlrev_b32_e32 v28, 16, v236
	v_and_b32_e32 v29, 0xffff0000, v236
	v_lshlrev_b32_e32 v30, 16, v237
	v_and_b32_e32 v31, 0xffff0000, v237
	v_cvt_pk_bf16_f32 v26, v26, v27
	v_cvt_pk_bf16_f32 v27, v32, v33
	v_lshlrev_b32_e32 v32, 16, v238
	v_and_b32_e32 v33, 0xffff0000, v238
	v_pk_add_f32 v[22:23], v[22:23], v[30:31]
	v_pk_add_f32 v[20:21], v[20:21], v[28:29]
	v_lshlrev_b32_e32 v34, 16, v239
	v_and_b32_e32 v35, 0xffff0000, v239
	v_pk_add_f32 v[30:31], v[16:17], v[32:33]
	v_mul_f32_e32 v16, v21, v21
	v_mul_f32_e32 v17, v23, v23
	v_pk_add_f32 v[28:29], v[18:19], v[34:35]
	v_fmac_f32_e32 v16, v20, v20
	v_fmac_f32_e32 v17, v22, v22
	v_add_f32_e32 v16, v16, v17
	v_mul_f32_e32 v17, v31, v31
	v_mul_f32_e32 v18, v29, v29
	v_fmac_f32_e32 v17, v30, v30
	v_fmac_f32_e32 v18, v28, v28
	v_add_f32_e32 v17, v17, v18
	v_add_f32_e32 v16, v16, v17
	v_add_f32_e32 v19, v36, v16
	v_mov_b32_e32 v34, v19
	v_lshl_add_u64 v[16:17], s[16:17], 0, v[94:95]
	v_lshl_add_u64 v[32:33], v[168:169], 1, v[16:17]
	global_store_dwordx4 v[32:33], v[24:27], off
	v_cvt_pk_bf16_f32 v18, v20, v21
	s_waitcnt lgkmcnt(0)
	v_permlane16_swap_b32_e32 v19, v34
	v_add_f32_e32 v16, v19, v34
	v_mov_b32_e32 v17, v16
	v_cvt_pk_bf16_f32 v19, v22, v23
	v_cvt_pk_bf16_f32 v20, v30, v31
	v_cvt_pk_bf16_f32 v21, v28, v29
	global_store_dwordx4 v[32:33], v[18:21], off offset:256
	v_permlane32_swap_b32_e32 v16, v17
	v_add_f32_e32 v16, v16, v17
	s_and_saveexec_b64 s[4:5], s[6:7]
	s_cbranch_execz .LBB0_418
	v_lshlrev_b64 v[18:19], 6, v[92:93]
	v_lshl_add_u64 v[18:19], s[22:23], 0, v[18:19]
	v_lshl_add_u64 v[18:19], s[40:41], 2, v[18:19]
	s_lshl_b32 s10, s51, 2
	v_lshl_add_u64 v[18:19], v[18:19], 0, s[10:11]
	global_store_dword v[18:19], v16, off
.LBB0_418:
	s_or_b64 exec, exec, s[4:5]
	s_waitcnt vmcnt(15)
	v_lshlrev_b32_e32 v16, 16, v240
	s_waitcnt lgkmcnt(0)
	v_and_b32_e32 v17, 0xffff0000, v240
	v_lshlrev_b32_e32 v18, 16, v241
	v_and_b32_e32 v19, 0xffff0000, v241
	v_lshlrev_b32_e32 v20, 16, v242
	v_and_b32_e32 v21, 0xffff0000, v242
	v_lshlrev_b32_e32 v22, 16, v243
	v_and_b32_e32 v23, 0xffff0000, v243
	v_pk_add_f32 v[14:15], v[14:15], v[18:19]
	v_pk_add_f32 v[12:13], v[12:13], v[16:17]
	v_pk_add_f32 v[16:17], v[10:11], v[22:23]
	v_pk_add_f32 v[10:11], v[8:9], v[20:21]
	v_mul_f32_e32 v8, v13, v13
	v_mul_f32_e32 v9, v15, v15
	v_fmac_f32_e32 v8, v12, v12
	v_fmac_f32_e32 v9, v14, v14
	v_add_f32_e32 v8, v8, v9
	v_mul_f32_e32 v9, v11, v11
	v_mul_f32_e32 v18, v17, v17
	v_fmac_f32_e32 v9, v10, v10
	v_fmac_f32_e32 v18, v16, v16
	v_add_f32_e32 v9, v9, v18
	v_add_f32_e32 v20, v8, v9
	v_cvt_pk_bf16_f32 v8, v12, v13
	v_cvt_pk_bf16_f32 v9, v14, v15
	s_waitcnt vmcnt(14)
	v_lshlrev_b32_e32 v12, 16, v244
	v_and_b32_e32 v13, 0xffff0000, v244
	v_lshlrev_b32_e32 v14, 16, v245
	v_and_b32_e32 v15, 0xffff0000, v245
	v_cvt_pk_bf16_f32 v10, v10, v11
	v_cvt_pk_bf16_f32 v11, v16, v17
	v_lshlrev_b32_e32 v16, 16, v246
	v_and_b32_e32 v17, 0xffff0000, v246
	v_pk_add_f32 v[6:7], v[6:7], v[14:15]
	v_pk_add_f32 v[4:5], v[4:5], v[12:13]
	v_lshlrev_b32_e32 v18, 16, v247
	v_and_b32_e32 v19, 0xffff0000, v247
	v_pk_add_f32 v[14:15], v[0:1], v[16:17]
	v_mul_f32_e32 v0, v5, v5
	v_mul_f32_e32 v1, v7, v7
	v_pk_add_f32 v[12:13], v[2:3], v[18:19]
	v_fmac_f32_e32 v0, v4, v4
	v_fmac_f32_e32 v1, v6, v6
	v_add_f32_e32 v0, v0, v1
	v_mul_f32_e32 v1, v15, v15
	v_mul_f32_e32 v2, v13, v13
	v_fmac_f32_e32 v1, v14, v14
	v_fmac_f32_e32 v2, v12, v12
	v_add_f32_e32 v1, v1, v2
	v_add_f32_e32 v0, v0, v1
	v_add_f32_e32 v3, v20, v0
	v_mov_b32_e32 v18, v3
	v_lshl_add_u64 v[0:1], s[16:17], 0, v[90:91]
	v_lshl_add_u64 v[16:17], v[168:169], 1, v[0:1]
	global_store_dwordx4 v[16:17], v[8:11], off
	v_cvt_pk_bf16_f32 v2, v4, v5
	s_waitcnt lgkmcnt(0)
	v_permlane16_swap_b32_e32 v3, v18
	v_add_f32_e32 v0, v3, v18
	v_mov_b32_e32 v1, v0
	v_cvt_pk_bf16_f32 v3, v6, v7
	v_cvt_pk_bf16_f32 v4, v14, v15
	v_cvt_pk_bf16_f32 v5, v12, v13
	global_store_dwordx4 v[16:17], v[2:5], off offset:256
	v_permlane32_swap_b32_e32 v0, v1
	v_add_f32_e32 v0, v0, v1
	s_and_saveexec_b64 s[4:5], s[6:7]
	s_cbranch_execz .LBB0_420
	v_lshlrev_b64 v[2:3], 6, v[88:89]
	v_lshl_add_u64 v[2:3], s[22:23], 0, v[2:3]
	v_lshl_add_u64 v[2:3], s[40:41], 2, v[2:3]
	s_lshl_b32 s10, s51, 2
	v_lshl_add_u64 v[2:3], v[2:3], 0, s[10:11]
	global_store_dword v[2:3], v0, off

.LBB0_562:
	v_lshl_or_b32 v168, s12, 8, v188
	v_lshl_add_u32 v172, s54, 8, v186
	v_ashrrev_i32_e32 v169, 31, v168
	v_lshlrev_b64 v[204:205], 1, v[168:169]
	v_ashrrev_i32_e32 v173, 31, v172
	v_lshl_add_u64 v[170:171], s[26:27], 0, v[204:205]
	v_lshlrev_b64 v[206:207], 11, v[172:173]
	v_lshl_add_u64 v[128:129], v[170:171], 0, v[206:207]
	global_load_dwordx4 v[194:197], v[128:129], off
	global_load_dwordx4 v[198:201], v[128:129], off offset:256
	v_or_b32_e32 v182, 16, v172
	v_or_b32_e32 v178, 32, v172
	v_or_b32_e32 v174, 48, v172
	v_ashrrev_i32_e32 v183, 31, v182
	v_ashrrev_i32_e32 v179, 31, v178
	v_ashrrev_i32_e32 v175, 31, v174
	v_lshlrev_b64 v[184:185], 11, v[182:183]
	v_lshlrev_b64 v[180:181], 11, v[178:179]
	v_lshlrev_b64 v[176:177], 11, v[174:175]
	v_lshl_add_u64 v[128:129], v[170:171], 0, v[184:185]
	v_lshl_add_u64 v[130:131], v[170:171], 0, v[180:181]
	v_lshl_add_u64 v[208:209], v[170:171], 0, v[176:177]
	global_load_dwordx4 v[148:151], v[128:129], off
	global_load_dwordx4 v[144:147], v[128:129], off offset:256
	global_load_dwordx4 v[140:143], v[130:131], off
	global_load_dwordx4 v[136:139], v[130:131], off offset:256
	global_load_dwordx4 v[132:135], v[208:209], off
	s_nop 0
	global_load_dwordx4 v[128:131], v[208:209], off offset:256
	v_add_u32_e32 v248, 0x80, v172
	v_ashrrev_i32_e32 v249, 31, v248
	v_lshlrev_b64 v[248:249], 11, v[248:249]
	v_lshl_add_u64 v[248:249], v[170:171], 0, v[248:249]
	global_load_dwordx4 v[216:219], v[248:249], off
	global_load_dwordx4 v[220:223], v[248:249], off offset:256
	v_add_u32_e32 v250, 0x90, v172
	v_ashrrev_i32_e32 v251, 31, v250
	v_lshlrev_b64 v[250:251], 11, v[250:251]
	v_lshl_add_u64 v[250:251], v[170:171], 0, v[250:251]
	global_load_dwordx4 v[224:227], v[250:251], off
	global_load_dwordx4 v[228:231], v[250:251], off offset:256
	v_add_u32_e32 v252, 0xa0, v172
	v_ashrrev_i32_e32 v253, 31, v252
	v_lshlrev_b64 v[252:253], 11, v[252:253]
	v_lshl_add_u64 v[252:253], v[170:171], 0, v[252:253]
	global_load_dwordx4 v[232:235], v[252:253], off
	global_load_dwordx4 v[236:239], v[252:253], off offset:256
	v_add_u32_e32 v248, 0xb0, v172
	v_ashrrev_i32_e32 v249, 31, v248
	v_lshlrev_b64 v[248:249], 11, v[248:249]
	v_lshl_add_u64 v[248:249], v[170:171], 0, v[248:249]
	global_load_dwordx4 v[240:243], v[248:249], off
	global_load_dwordx4 v[244:247], v[248:249], off offset:256
	v_and_b32_e32 v208, 64, v192
	v_xor_b32_e32 v193, 16, v192
	v_add_u32_e32 v208, 64, v208
	v_xor_b32_e32 v209, 32, v192
	v_cmp_lt_i32_e32 vcc, v193, v208
	v_lshl_add_u64 v[206:207], s[26:27], 0, v[206:207]
	v_lshl_add_u64 v[204:205], v[206:207], 0, v[204:205]
	v_cndmask_b32_e32 v193, v192, v193, vcc
	v_cmp_lt_i32_e32 vcc, v209, v208
	v_lshlrev_b32_e32 v193, 2, v193
	s_lshl_b32 s38, s12, 2
	v_cndmask_b32_e32 v214, v192, v209, vcc
	s_ashr_i32 s39, s38, 31
	s_waitcnt vmcnt(8)
	v_lshlrev_b32_e32 v206, 16, v194
	v_and_b32_e32 v207, 0xffff0000, v194
	v_lshlrev_b32_e32 v194, 16, v195
	v_and_b32_e32 v195, 0xffff0000, v195
	v_lshlrev_b32_e32 v208, 16, v196
	v_and_b32_e32 v209, 0xffff0000, v196
	v_lshlrev_b32_e32 v196, 16, v197
	v_and_b32_e32 v197, 0xffff0000, v197
	v_lshlrev_b32_e32 v210, 16, v198
	v_and_b32_e32 v211, 0xffff0000, v198
	v_lshlrev_b32_e32 v198, 16, v199
	v_and_b32_e32 v199, 0xffff0000, v199
	v_lshlrev_b32_e32 v212, 16, v200
	v_and_b32_e32 v213, 0xffff0000, v200
	v_lshlrev_b32_e32 v200, 16, v201
	v_and_b32_e32 v201, 0xffff0000, v201
	v_pk_add_f32 v[126:127], v[126:127], v[194:195]
	v_pk_add_f32 v[124:125], v[124:125], v[206:207]
	v_pk_add_f32 v[122:123], v[122:123], v[196:197]
	v_pk_add_f32 v[120:121], v[120:121], v[208:209]
	v_pk_add_f32 v[118:119], v[118:119], v[198:199]
	v_pk_add_f32 v[116:117], v[116:117], v[210:211]
	v_pk_add_f32 v[194:195], v[114:115], v[200:201]
	v_pk_add_f32 v[196:197], v[112:113], v[212:213]
	v_mul_f32_e32 v114, v125, v125
	v_mul_f32_e32 v115, v127, v127
	v_mul_f32_e32 v198, v121, v121
	v_mul_f32_e32 v199, v123, v123
	v_cvt_pk_bf16_f32 v112, v124, v125
	v_cvt_pk_bf16_f32 v113, v126, v127
	v_mul_f32_e32 v125, v117, v117
	v_mul_f32_e32 v127, v119, v119
	v_mul_f32_e32 v200, v197, v197
	v_mul_f32_e32 v201, v195, v195
	v_fmac_f32_e32 v114, v124, v124
	v_fmac_f32_e32 v115, v126, v126
	v_fmac_f32_e32 v198, v120, v120
	v_fmac_f32_e32 v199, v122, v122
	v_fmac_f32_e32 v125, v116, v116
	v_fmac_f32_e32 v127, v118, v118
	v_fmac_f32_e32 v200, v196, v196
	v_fmac_f32_e32 v201, v194, v194
	v_add_f32_e32 v114, v114, v115
	v_add_f32_e32 v115, v198, v199
	v_add_f32_e32 v124, v125, v127
	v_add_f32_e32 v125, v200, v201
	v_add_f32_e32 v114, v114, v115
	v_add_f32_e32 v115, v124, v125
	v_add_f32_e32 v124, v114, v115
	v_mov_b32_e32 v125, v124
	v_cvt_pk_bf16_f32 v114, v120, v121
	v_cvt_pk_bf16_f32 v115, v122, v123
	global_store_dwordx4 v[204:205], v[112:115], off
	v_cvt_pk_bf16_f32 v116, v116, v117
	v_cvt_pk_bf16_f32 v117, v118, v119
	v_cvt_pk_bf16_f32 v118, v196, v197
	v_cvt_pk_bf16_f32 v119, v194, v195
	global_store_dwordx4 v[204:205], v[116:119], off offset:256
	s_waitcnt lgkmcnt(0)
	v_permlane16_swap_b32_e32 v124, v125
	v_add_f32_e32 v113, v124, v125
	v_lshlrev_b32_e32 v112, 2, v214
	v_mov_b32_e32 v114, v113
	s_nop 1
	v_permlane32_swap_b32_e32 v113, v114
	v_add_f32_e32 v113, v113, v114
	s_and_saveexec_b64 s[4:5], s[6:7]
	s_cbranch_execz .LBB0_564
	v_lshlrev_b64 v[116:117], 6, v[172:173]
	v_lshl_add_u64 v[116:117], s[28:29], 0, v[116:117]
	v_lshl_add_u64 v[116:117], s[38:39], 2, v[116:117]
	s_lshl_b32 s12, s47, 2
	v_lshl_add_u64 v[116:117], v[116:117], 0, s[12:13]
	global_store_dword v[116:117], v113, off
.LBB0_564:
	s_or_b64 exec, exec, s[4:5]
	s_waitcnt lgkmcnt(0)
	v_lshlrev_b32_e32 v114, 16, v148
	v_and_b32_e32 v115, 0xffff0000, v148
	v_lshlrev_b32_e32 v116, 16, v149
	v_and_b32_e32 v117, 0xffff0000, v149
	v_lshlrev_b32_e32 v118, 16, v150
	v_and_b32_e32 v119, 0xffff0000, v150
	v_lshlrev_b32_e32 v120, 16, v151
	v_and_b32_e32 v121, 0xffff0000, v151
	v_pk_add_f32 v[110:111], v[110:111], v[116:117]
	v_pk_add_f32 v[108:109], v[108:109], v[114:115]
	v_pk_add_f32 v[114:115], v[106:107], v[120:121]
	v_pk_add_f32 v[106:107], v[104:105], v[118:119]
	v_mul_f32_e32 v104, v109, v109
	v_mul_f32_e32 v105, v111, v111
	v_fmac_f32_e32 v104, v108, v108
	v_fmac_f32_e32 v105, v110, v110
	v_add_f32_e32 v104, v104, v105
	v_mul_f32_e32 v105, v107, v107
	v_mul_f32_e32 v113, v115, v115
	v_fmac_f32_e32 v105, v106, v106
	v_fmac_f32_e32 v113, v114, v114
	v_add_f32_e32 v105, v105, v113
	v_add_f32_e32 v113, v104, v105
	v_cvt_pk_bf16_f32 v104, v108, v109
	v_cvt_pk_bf16_f32 v105, v110, v111
	v_lshlrev_b32_e32 v108, 16, v144
	v_and_b32_e32 v109, 0xffff0000, v144
	v_lshlrev_b32_e32 v110, 16, v145
	v_and_b32_e32 v111, 0xffff0000, v145
	v_cvt_pk_bf16_f32 v106, v106, v107
	v_cvt_pk_bf16_f32 v107, v114, v115
	v_lshlrev_b32_e32 v114, 16, v146
	v_and_b32_e32 v115, 0xffff0000, v146
	v_pk_add_f32 v[102:103], v[102:103], v[110:111]
	v_pk_add_f32 v[100:101], v[100:101], v[108:109]
	v_lshlrev_b32_e32 v116, 16, v147
	v_and_b32_e32 v117, 0xffff0000, v147
	v_pk_add_f32 v[110:111], v[96:97], v[114:115]
	v_mul_f32_e32 v96, v101, v101
	v_mul_f32_e32 v97, v103, v103
	v_pk_add_f32 v[108:109], v[98:99], v[116:117]
	v_fmac_f32_e32 v96, v100, v100
	v_fmac_f32_e32 v97, v102, v102
	v_add_f32_e32 v96, v96, v97
	v_mul_f32_e32 v97, v111, v111
	v_mul_f32_e32 v98, v109, v109
	v_fmac_f32_e32 v97, v110, v110
	v_fmac_f32_e32 v98, v108, v108
	v_add_f32_e32 v97, v97, v98
	v_add_f32_e32 v96, v96, v97
	v_add_f32_e32 v99, v113, v96
	v_mov_b32_e32 v113, v99
	v_lshl_add_u64 v[96:97], s[26:27], 0, v[184:185]
	v_lshl_add_u64 v[114:115], v[168:169], 1, v[96:97]
	global_store_dwordx4 v[114:115], v[104:107], off
	v_cvt_pk_bf16_f32 v98, v100, v101
	s_waitcnt lgkmcnt(0)
	v_permlane16_swap_b32_e32 v99, v113
	v_add_f32_e32 v96, v99, v113
	v_mov_b32_e32 v97, v96
	v_cvt_pk_bf16_f32 v99, v102, v103
	v_cvt_pk_bf16_f32 v100, v110, v111
	v_cvt_pk_bf16_f32 v101, v108, v109
	global_store_dwordx4 v[114:115], v[98:101], off offset:256
	v_permlane32_swap_b32_e32 v96, v97
	v_add_f32_e32 v96, v96, v97
	s_and_saveexec_b64 s[4:5], s[6:7]
	s_cbranch_execz .LBB0_566
	v_lshlrev_b64 v[98:99], 6, v[182:183]
	v_lshl_add_u64 v[98:99], s[28:29], 0, v[98:99]
	v_lshl_add_u64 v[98:99], s[38:39], 2, v[98:99]
	s_lshl_b32 s12, s47, 2
	v_lshl_add_u64 v[98:99], v[98:99], 0, s[12:13]
	global_store_dword v[98:99], v96, off
.LBB0_566:
	s_or_b64 exec, exec, s[4:5]
	v_lshlrev_b32_e32 v96, 16, v140
	s_waitcnt lgkmcnt(0)
	v_and_b32_e32 v97, 0xffff0000, v140
	v_lshlrev_b32_e32 v98, 16, v141
	v_and_b32_e32 v99, 0xffff0000, v141
	v_lshlrev_b32_e32 v100, 16, v142
	v_and_b32_e32 v101, 0xffff0000, v142
	v_lshlrev_b32_e32 v102, 16, v143
	v_and_b32_e32 v103, 0xffff0000, v143
	v_pk_add_f32 v[94:95], v[94:95], v[98:99]
	v_pk_add_f32 v[92:93], v[92:93], v[96:97]
	v_pk_add_f32 v[96:97], v[90:91], v[102:103]
	v_pk_add_f32 v[90:91], v[88:89], v[100:101]
	v_mul_f32_e32 v88, v93, v93
	v_mul_f32_e32 v89, v95, v95
	v_fmac_f32_e32 v88, v92, v92
	v_fmac_f32_e32 v89, v94, v94
	v_add_f32_e32 v88, v88, v89
	v_mul_f32_e32 v89, v91, v91
	v_mul_f32_e32 v98, v97, v97
	v_fmac_f32_e32 v89, v90, v90
	v_fmac_f32_e32 v98, v96, v96
	v_add_f32_e32 v89, v89, v98
	v_add_f32_e32 v100, v88, v89
	v_cvt_pk_bf16_f32 v88, v92, v93
	v_cvt_pk_bf16_f32 v89, v94, v95
	v_lshlrev_b32_e32 v92, 16, v136
	v_and_b32_e32 v93, 0xffff0000, v136
	v_lshlrev_b32_e32 v94, 16, v137
	v_and_b32_e32 v95, 0xffff0000, v137
	v_cvt_pk_bf16_f32 v90, v90, v91
	v_cvt_pk_bf16_f32 v91, v96, v97
	v_lshlrev_b32_e32 v96, 16, v138
	v_and_b32_e32 v97, 0xffff0000, v138
	v_pk_add_f32 v[86:87], v[86:87], v[94:95]
	v_pk_add_f32 v[84:85], v[84:85], v[92:93]
	v_lshlrev_b32_e32 v98, 16, v139
	v_and_b32_e32 v99, 0xffff0000, v139
	v_pk_add_f32 v[94:95], v[80:81], v[96:97]
	v_mul_f32_e32 v80, v85, v85
	v_mul_f32_e32 v81, v87, v87
	v_pk_add_f32 v[92:93], v[82:83], v[98:99]
	v_fmac_f32_e32 v80, v84, v84
	v_fmac_f32_e32 v81, v86, v86
	v_add_f32_e32 v80, v80, v81
	v_mul_f32_e32 v81, v95, v95
	v_mul_f32_e32 v82, v93, v93
	v_fmac_f32_e32 v81, v94, v94
	v_fmac_f32_e32 v82, v92, v92
	v_add_f32_e32 v81, v81, v82
	v_add_f32_e32 v80, v80, v81
	v_add_f32_e32 v83, v100, v80
	v_mov_b32_e32 v98, v83
	v_lshl_add_u64 v[80:81], s[26:27], 0, v[180:181]
	v_lshl_add_u64 v[96:97], v[168:169], 1, v[80:81]
	global_store_dwordx4 v[96:97], v[88:91], off
	v_cvt_pk_bf16_f32 v82, v84, v85
	s_waitcnt lgkmcnt(0)
	v_permlane16_swap_b32_e32 v83, v98
	v_add_f32_e32 v80, v83, v98
	v_mov_b32_e32 v81, v80
	v_cvt_pk_bf16_f32 v83, v86, v87
	v_cvt_pk_bf16_f32 v84, v94, v95
	v_cvt_pk_bf16_f32 v85, v92, v93
	global_store_dwordx4 v[96:97], v[82:85], off offset:256
	v_permlane32_swap_b32_e32 v80, v81
	v_add_f32_e32 v80, v80, v81
	s_and_saveexec_b64 s[4:5], s[6:7]
	s_cbranch_execz .LBB0_568
	v_lshlrev_b64 v[82:83], 6, v[178:179]
	v_lshl_add_u64 v[82:83], s[28:29], 0, v[82:83]
	v_lshl_add_u64 v[82:83], s[38:39], 2, v[82:83]
	s_lshl_b32 s12, s47, 2
	v_lshl_add_u64 v[82:83], v[82:83], 0, s[12:13]
	global_store_dword v[82:83], v80, off
.LBB0_568:
	s_or_b64 exec, exec, s[4:5]
	v_lshlrev_b32_e32 v80, 16, v132
	s_waitcnt lgkmcnt(0)
	v_and_b32_e32 v81, 0xffff0000, v132
	v_lshlrev_b32_e32 v82, 16, v133
	v_and_b32_e32 v83, 0xffff0000, v133
	v_lshlrev_b32_e32 v84, 16, v134
	v_and_b32_e32 v85, 0xffff0000, v134
	v_lshlrev_b32_e32 v86, 16, v135
	v_and_b32_e32 v87, 0xffff0000, v135
	v_pk_add_f32 v[78:79], v[78:79], v[82:83]
	v_pk_add_f32 v[76:77], v[76:77], v[80:81]
	v_pk_add_f32 v[80:81], v[74:75], v[86:87]
	v_pk_add_f32 v[74:75], v[72:73], v[84:85]
	v_mul_f32_e32 v72, v77, v77
	v_mul_f32_e32 v73, v79, v79
	v_fmac_f32_e32 v72, v76, v76
	v_fmac_f32_e32 v73, v78, v78
	v_add_f32_e32 v72, v72, v73
	v_mul_f32_e32 v73, v75, v75
	v_mul_f32_e32 v82, v81, v81
	v_fmac_f32_e32 v73, v74, v74
	v_fmac_f32_e32 v82, v80, v80
	v_add_f32_e32 v73, v73, v82
	v_add_f32_e32 v84, v72, v73
	v_cvt_pk_bf16_f32 v72, v76, v77
	v_cvt_pk_bf16_f32 v73, v78, v79
	v_lshlrev_b32_e32 v76, 16, v128
	v_and_b32_e32 v77, 0xffff0000, v128
	v_lshlrev_b32_e32 v78, 16, v129
	v_and_b32_e32 v79, 0xffff0000, v129
	v_cvt_pk_bf16_f32 v74, v74, v75
	v_cvt_pk_bf16_f32 v75, v80, v81
	v_lshlrev_b32_e32 v80, 16, v130
	v_and_b32_e32 v81, 0xffff0000, v130
	v_pk_add_f32 v[70:71], v[70:71], v[78:79]
	v_pk_add_f32 v[68:69], v[68:69], v[76:77]
	v_lshlrev_b32_e32 v82, 16, v131
	v_and_b32_e32 v83, 0xffff0000, v131
	v_pk_add_f32 v[78:79], v[64:65], v[80:81]
	v_mul_f32_e32 v64, v69, v69
	v_mul_f32_e32 v65, v71, v71
	v_pk_add_f32 v[76:77], v[66:67], v[82:83]
	v_fmac_f32_e32 v64, v68, v68
	v_fmac_f32_e32 v65, v70, v70
	v_add_f32_e32 v64, v64, v65
	v_mul_f32_e32 v65, v79, v79
	v_mul_f32_e32 v66, v77, v77
	v_fmac_f32_e32 v65, v78, v78
	v_fmac_f32_e32 v66, v76, v76
	v_add_f32_e32 v65, v65, v66
	v_add_f32_e32 v64, v64, v65
	v_add_f32_e32 v67, v84, v64
	v_mov_b32_e32 v82, v67
	v_lshl_add_u64 v[64:65], s[26:27], 0, v[176:177]
	v_lshl_add_u64 v[80:81], v[168:169], 1, v[64:65]
	global_store_dwordx4 v[80:81], v[72:75], off
	v_cvt_pk_bf16_f32 v66, v68, v69
	s_waitcnt lgkmcnt(0)
	v_permlane16_swap_b32_e32 v67, v82
	v_add_f32_e32 v64, v67, v82
	v_mov_b32_e32 v65, v64
	v_cvt_pk_bf16_f32 v67, v70, v71
	v_cvt_pk_bf16_f32 v68, v78, v79
	v_cvt_pk_bf16_f32 v69, v76, v77
	global_store_dwordx4 v[80:81], v[66:69], off offset:256
	v_permlane32_swap_b32_e32 v64, v65
	v_add_f32_e32 v64, v64, v65
	s_and_saveexec_b64 s[4:5], s[6:7]
	s_cbranch_execz .LBB0_570
	v_lshlrev_b64 v[66:67], 6, v[174:175]
	v_lshl_add_u64 v[66:67], s[28:29], 0, v[66:67]
	v_lshl_add_u64 v[66:67], s[38:39], 2, v[66:67]
	s_lshl_b32 s12, s47, 2
	v_lshl_add_u64 v[66:67], v[66:67], 0, s[12:13]
	global_store_dword v[66:67], v64, off
.LBB0_570:
	s_or_b64 exec, exec, s[4:5]
	v_add_u32_e32 v100, 0x80, v172
	v_ashrrev_i32_e32 v101, 31, v100
	v_lshlrev_b64 v[110:111], 11, v[100:101]
	s_waitcnt lgkmcnt(0)
	v_lshl_add_u64 v[64:65], v[170:171], 0, v[110:111]
	v_add_u32_e32 v96, 0x90, v172
	v_add_u32_e32 v92, 0xa0, v172
	v_add_u32_e32 v88, 0xb0, v172
	v_ashrrev_i32_e32 v97, 31, v96
	v_ashrrev_i32_e32 v93, 31, v92
	v_ashrrev_i32_e32 v89, 31, v88
	v_lshlrev_b64 v[98:99], 11, v[96:97]
	v_lshlrev_b64 v[94:95], 11, v[92:93]
	v_lshlrev_b64 v[90:91], 11, v[88:89]
	v_lshl_add_u64 v[64:65], v[170:171], 0, v[98:99]
	v_lshl_add_u64 v[66:67], v[170:171], 0, v[94:95]
	v_lshl_add_u64 v[114:115], v[170:171], 0, v[90:91]
	s_waitcnt vmcnt(15)
	v_lshlrev_b32_e32 v114, 16, v216
	v_and_b32_e32 v115, 0xffff0000, v216
	v_lshlrev_b32_e32 v102, 16, v217
	v_and_b32_e32 v103, 0xffff0000, v217
	v_lshlrev_b32_e32 v116, 16, v218
	v_and_b32_e32 v117, 0xffff0000, v218
	v_lshlrev_b32_e32 v104, 16, v219
	v_and_b32_e32 v105, 0xffff0000, v219
	s_waitcnt vmcnt(14)
	v_lshlrev_b32_e32 v118, 16, v220
	v_and_b32_e32 v119, 0xffff0000, v220
	v_lshlrev_b32_e32 v106, 16, v221
	v_and_b32_e32 v107, 0xffff0000, v221
	v_lshlrev_b32_e32 v120, 16, v222
	v_and_b32_e32 v121, 0xffff0000, v222
	v_lshlrev_b32_e32 v108, 16, v223
	v_and_b32_e32 v109, 0xffff0000, v223
	v_pk_add_f32 v[62:63], v[62:63], v[102:103]
	v_pk_add_f32 v[60:61], v[60:61], v[114:115]
	v_pk_add_f32 v[58:59], v[58:59], v[104:105]
	v_pk_add_f32 v[56:57], v[56:57], v[116:117]
	v_pk_add_f32 v[54:55], v[54:55], v[106:107]
	v_pk_add_f32 v[52:53], v[52:53], v[118:119]
	v_pk_add_f32 v[102:103], v[50:51], v[108:109]
	v_pk_add_f32 v[104:105], v[48:49], v[120:121]
	v_mul_f32_e32 v106, v61, v61
	v_mul_f32_e32 v107, v63, v63
	v_mul_f32_e32 v108, v57, v57
	v_mul_f32_e32 v109, v59, v59
	v_cvt_pk_bf16_f32 v48, v60, v61
	v_cvt_pk_bf16_f32 v49, v62, v63
	v_cvt_pk_bf16_f32 v50, v56, v57
	v_cvt_pk_bf16_f32 v51, v58, v59
	v_mul_f32_e32 v57, v53, v53
	v_mul_f32_e32 v59, v55, v55
	v_mul_f32_e32 v61, v105, v105
	v_mul_f32_e32 v63, v103, v103
	v_fmac_f32_e32 v106, v60, v60
	v_fmac_f32_e32 v107, v62, v62
	v_fmac_f32_e32 v108, v56, v56
	v_fmac_f32_e32 v109, v58, v58
	v_fmac_f32_e32 v57, v52, v52
	v_fmac_f32_e32 v59, v54, v54
	v_fmac_f32_e32 v61, v104, v104
	v_fmac_f32_e32 v63, v102, v102
	v_add_f32_e32 v56, v106, v107
	v_add_f32_e32 v58, v108, v109
	v_add_f32_e32 v57, v57, v59
	v_add_f32_e32 v59, v61, v63
	v_add_f32_e32 v56, v56, v58
	v_add_f32_e32 v57, v57, v59
	v_add_f32_e32 v58, v56, v57
	v_mov_b32_e32 v59, v58
	v_lshl_add_u64 v[56:57], s[26:27], 0, v[110:111]
	v_lshl_add_u64 v[56:57], v[168:169], 1, v[56:57]
	global_store_dwordx4 v[56:57], v[48:51], off
	s_waitcnt lgkmcnt(0)
	s_nop 0
	v_permlane16_swap_b32_e32 v58, v59
	v_add_f32_e32 v48, v58, v59
	v_mov_b32_e32 v49, v48
	v_cvt_pk_bf16_f32 v50, v52, v53
	v_cvt_pk_bf16_f32 v51, v54, v55
	v_cvt_pk_bf16_f32 v52, v104, v105
	v_cvt_pk_bf16_f32 v53, v102, v103
	global_store_dwordx4 v[56:57], v[50:53], off offset:256
	v_permlane32_swap_b32_e32 v48, v49
	v_add_f32_e32 v48, v48, v49
	s_and_saveexec_b64 s[4:5], s[6:7]
	s_cbranch_execz .LBB0_572
	v_lshlrev_b64 v[50:51], 6, v[100:101]
	v_lshl_add_u64 v[50:51], s[28:29], 0, v[50:51]
	v_lshl_add_u64 v[50:51], s[38:39], 2, v[50:51]
	s_lshl_b32 s12, s47, 2
	v_lshl_add_u64 v[50:51], v[50:51], 0, s[12:13]
	global_store_dword v[50:51], v48, off
.LBB0_572:
	s_or_b64 exec, exec, s[4:5]
	s_waitcnt vmcnt(15)
	v_lshlrev_b32_e32 v48, 16, v224
	s_waitcnt lgkmcnt(0)
	v_and_b32_e32 v49, 0xffff0000, v224
	v_lshlrev_b32_e32 v50, 16, v225
	v_and_b32_e32 v51, 0xffff0000, v225
	v_lshlrev_b32_e32 v52, 16, v226
	v_and_b32_e32 v53, 0xffff0000, v226
	v_lshlrev_b32_e32 v54, 16, v227
	v_and_b32_e32 v55, 0xffff0000, v227
	v_pk_add_f32 v[46:47], v[46:47], v[50:51]
	v_pk_add_f32 v[44:45], v[44:45], v[48:49]
	v_pk_add_f32 v[48:49], v[42:43], v[54:55]
	v_pk_add_f32 v[42:43], v[40:41], v[52:53]
	v_mul_f32_e32 v40, v45, v45
	v_mul_f32_e32 v41, v47, v47
	v_fmac_f32_e32 v40, v44, v44
	v_fmac_f32_e32 v41, v46, v46
	v_add_f32_e32 v40, v40, v41
	v_mul_f32_e32 v41, v43, v43
	v_mul_f32_e32 v50, v49, v49
	v_fmac_f32_e32 v41, v42, v42
	v_fmac_f32_e32 v50, v48, v48
	v_add_f32_e32 v41, v41, v50
	v_add_f32_e32 v52, v40, v41
	v_cvt_pk_bf16_f32 v40, v44, v45
	v_cvt_pk_bf16_f32 v41, v46, v47
	s_waitcnt vmcnt(14)
	v_lshlrev_b32_e32 v44, 16, v228
	v_and_b32_e32 v45, 0xffff0000, v228
	v_lshlrev_b32_e32 v46, 16, v229
	v_and_b32_e32 v47, 0xffff0000, v229
	v_cvt_pk_bf16_f32 v42, v42, v43
	v_cvt_pk_bf16_f32 v43, v48, v49
	v_lshlrev_b32_e32 v48, 16, v230
	v_and_b32_e32 v49, 0xffff0000, v230
	v_pk_add_f32 v[38:39], v[38:39], v[46:47]
	v_pk_add_f32 v[36:37], v[36:37], v[44:45]
	v_lshlrev_b32_e32 v50, 16, v231
	v_and_b32_e32 v51, 0xffff0000, v231
	v_pk_add_f32 v[46:47], v[32:33], v[48:49]
	v_mul_f32_e32 v32, v37, v37
	v_mul_f32_e32 v33, v39, v39
	v_pk_add_f32 v[44:45], v[34:35], v[50:51]
	v_fmac_f32_e32 v32, v36, v36
	v_fmac_f32_e32 v33, v38, v38
	v_add_f32_e32 v32, v32, v33
	v_mul_f32_e32 v33, v47, v47
	v_mul_f32_e32 v34, v45, v45
	v_fmac_f32_e32 v33, v46, v46
	v_fmac_f32_e32 v34, v44, v44
	v_add_f32_e32 v33, v33, v34
	v_add_f32_e32 v32, v32, v33
	v_add_f32_e32 v35, v52, v32
	v_mov_b32_e32 v50, v35
	v_lshl_add_u64 v[32:33], s[26:27], 0, v[98:99]
	v_lshl_add_u64 v[48:49], v[168:169], 1, v[32:33]
	global_store_dwordx4 v[48:49], v[40:43], off
	v_cvt_pk_bf16_f32 v34, v36, v37
	s_waitcnt lgkmcnt(0)
	v_permlane16_swap_b32_e32 v35, v50
	v_add_f32_e32 v32, v35, v50
	v_mov_b32_e32 v33, v32
	v_cvt_pk_bf16_f32 v35, v38, v39
	v_cvt_pk_bf16_f32 v36, v46, v47
	v_cvt_pk_bf16_f32 v37, v44, v45
	global_store_dwordx4 v[48:49], v[34:37], off offset:256
	v_permlane32_swap_b32_e32 v32, v33
	v_add_f32_e32 v32, v32, v33
	s_and_saveexec_b64 s[4:5], s[6:7]
	s_cbranch_execz .LBB0_574
	v_lshlrev_b64 v[34:35], 6, v[96:97]
	v_lshl_add_u64 v[34:35], s[28:29], 0, v[34:35]
	v_lshl_add_u64 v[34:35], s[38:39], 2, v[34:35]
	s_lshl_b32 s12, s47, 2
	v_lshl_add_u64 v[34:35], v[34:35], 0, s[12:13]
	global_store_dword v[34:35], v32, off
.LBB0_574:
	s_or_b64 exec, exec, s[4:5]
	s_waitcnt vmcnt(15)
	v_lshlrev_b32_e32 v32, 16, v232
	s_waitcnt lgkmcnt(0)
	v_and_b32_e32 v33, 0xffff0000, v232
	v_lshlrev_b32_e32 v34, 16, v233
	v_and_b32_e32 v35, 0xffff0000, v233
	v_lshlrev_b32_e32 v36, 16, v234
	v_and_b32_e32 v37, 0xffff0000, v234
	v_lshlrev_b32_e32 v38, 16, v235
	v_and_b32_e32 v39, 0xffff0000, v235
	v_pk_add_f32 v[30:31], v[30:31], v[34:35]
	v_pk_add_f32 v[28:29], v[28:29], v[32:33]
	v_pk_add_f32 v[32:33], v[26:27], v[38:39]
	v_pk_add_f32 v[26:27], v[24:25], v[36:37]
	v_mul_f32_e32 v24, v29, v29
	v_mul_f32_e32 v25, v31, v31
	v_fmac_f32_e32 v24, v28, v28
	v_fmac_f32_e32 v25, v30, v30
	v_add_f32_e32 v24, v24, v25
	v_mul_f32_e32 v25, v27, v27
	v_mul_f32_e32 v34, v33, v33
	v_fmac_f32_e32 v25, v26, v26
	v_fmac_f32_e32 v34, v32, v32
	v_add_f32_e32 v25, v25, v34
	v_add_f32_e32 v36, v24, v25
	v_cvt_pk_bf16_f32 v24, v28, v29
	v_cvt_pk_bf16_f32 v25, v30, v31
	s_waitcnt vmcnt(14)
	v_lshlrev_b32_e32 v28, 16, v236
	v_and_b32_e32 v29, 0xffff0000, v236
	v_lshlrev_b32_e32 v30, 16, v237
	v_and_b32_e32 v31, 0xffff0000, v237
	v_cvt_pk_bf16_f32 v26, v26, v27
	v_cvt_pk_bf16_f32 v27, v32, v33
	v_lshlrev_b32_e32 v32, 16, v238
	v_and_b32_e32 v33, 0xffff0000, v238
	v_pk_add_f32 v[22:23], v[22:23], v[30:31]
	v_pk_add_f32 v[20:21], v[20:21], v[28:29]
	v_lshlrev_b32_e32 v34, 16, v239
	v_and_b32_e32 v35, 0xffff0000, v239
	v_pk_add_f32 v[30:31], v[16:17], v[32:33]
	v_mul_f32_e32 v16, v21, v21
	v_mul_f32_e32 v17, v23, v23
	v_pk_add_f32 v[28:29], v[18:19], v[34:35]
	v_fmac_f32_e32 v16, v20, v20
	v_fmac_f32_e32 v17, v22, v22
	v_add_f32_e32 v16, v16, v17
	v_mul_f32_e32 v17, v31, v31
	v_mul_f32_e32 v18, v29, v29
	v_fmac_f32_e32 v17, v30, v30
	v_fmac_f32_e32 v18, v28, v28
	v_add_f32_e32 v17, v17, v18
	v_add_f32_e32 v16, v16, v17
	v_add_f32_e32 v19, v36, v16
	v_mov_b32_e32 v34, v19
	v_lshl_add_u64 v[16:17], s[26:27], 0, v[94:95]
	v_lshl_add_u64 v[32:33], v[168:169], 1, v[16:17]
	global_store_dwordx4 v[32:33], v[24:27], off
	v_cvt_pk_bf16_f32 v18, v20, v21
	s_waitcnt lgkmcnt(0)
	v_permlane16_swap_b32_e32 v19, v34
	v_add_f32_e32 v16, v19, v34
	v_mov_b32_e32 v17, v16
	v_cvt_pk_bf16_f32 v19, v22, v23
	v_cvt_pk_bf16_f32 v20, v30, v31
	v_cvt_pk_bf16_f32 v21, v28, v29
	global_store_dwordx4 v[32:33], v[18:21], off offset:256
	v_permlane32_swap_b32_e32 v16, v17
	v_add_f32_e32 v16, v16, v17
	s_and_saveexec_b64 s[4:5], s[6:7]
	s_cbranch_execz .LBB0_576
	v_lshlrev_b64 v[18:19], 6, v[92:93]
	v_lshl_add_u64 v[18:19], s[28:29], 0, v[18:19]
	v_lshl_add_u64 v[18:19], s[38:39], 2, v[18:19]
	s_lshl_b32 s12, s47, 2
	v_lshl_add_u64 v[18:19], v[18:19], 0, s[12:13]
	global_store_dword v[18:19], v16, off
.LBB0_576:
	s_or_b64 exec, exec, s[4:5]
	s_waitcnt vmcnt(15)
	v_lshlrev_b32_e32 v16, 16, v240
	s_waitcnt lgkmcnt(0)
	v_and_b32_e32 v17, 0xffff0000, v240
	v_lshlrev_b32_e32 v18, 16, v241
	v_and_b32_e32 v19, 0xffff0000, v241
	v_lshlrev_b32_e32 v20, 16, v242
	v_and_b32_e32 v21, 0xffff0000, v242
	v_lshlrev_b32_e32 v22, 16, v243
	v_and_b32_e32 v23, 0xffff0000, v243
	v_pk_add_f32 v[14:15], v[14:15], v[18:19]
	v_pk_add_f32 v[12:13], v[12:13], v[16:17]
	v_pk_add_f32 v[16:17], v[10:11], v[22:23]
	v_pk_add_f32 v[10:11], v[8:9], v[20:21]
	v_mul_f32_e32 v8, v13, v13
	v_mul_f32_e32 v9, v15, v15
	v_fmac_f32_e32 v8, v12, v12
	v_fmac_f32_e32 v9, v14, v14
	v_add_f32_e32 v8, v8, v9
	v_mul_f32_e32 v9, v11, v11
	v_mul_f32_e32 v18, v17, v17
	v_fmac_f32_e32 v9, v10, v10
	v_fmac_f32_e32 v18, v16, v16
	v_add_f32_e32 v9, v9, v18
	v_add_f32_e32 v20, v8, v9
	v_cvt_pk_bf16_f32 v8, v12, v13
	v_cvt_pk_bf16_f32 v9, v14, v15
	s_waitcnt vmcnt(14)
	v_lshlrev_b32_e32 v12, 16, v244
	v_and_b32_e32 v13, 0xffff0000, v244
	v_lshlrev_b32_e32 v14, 16, v245
	v_and_b32_e32 v15, 0xffff0000, v245
	v_cvt_pk_bf16_f32 v10, v10, v11
	v_cvt_pk_bf16_f32 v11, v16, v17
	v_lshlrev_b32_e32 v16, 16, v246
	v_and_b32_e32 v17, 0xffff0000, v246
	v_pk_add_f32 v[6:7], v[6:7], v[14:15]
	v_pk_add_f32 v[4:5], v[4:5], v[12:13]
	v_lshlrev_b32_e32 v18, 16, v247
	v_and_b32_e32 v19, 0xffff0000, v247
	v_pk_add_f32 v[14:15], v[0:1], v[16:17]
	v_mul_f32_e32 v0, v5, v5
	v_mul_f32_e32 v1, v7, v7
	v_pk_add_f32 v[12:13], v[2:3], v[18:19]
	v_fmac_f32_e32 v0, v4, v4
	v_fmac_f32_e32 v1, v6, v6
	v_add_f32_e32 v0, v0, v1
	v_mul_f32_e32 v1, v15, v15
	v_mul_f32_e32 v2, v13, v13
	v_fmac_f32_e32 v1, v14, v14
	v_fmac_f32_e32 v2, v12, v12
	v_add_f32_e32 v1, v1, v2
	v_add_f32_e32 v0, v0, v1
	v_add_f32_e32 v3, v20, v0
	v_mov_b32_e32 v18, v3
	v_lshl_add_u64 v[0:1], s[26:27], 0, v[90:91]
	v_lshl_add_u64 v[16:17], v[168:169], 1, v[0:1]
	global_store_dwordx4 v[16:17], v[8:11], off
	v_cvt_pk_bf16_f32 v2, v4, v5
	s_waitcnt lgkmcnt(0)
	v_permlane16_swap_b32_e32 v3, v18
	v_add_f32_e32 v0, v3, v18
	v_mov_b32_e32 v1, v0
	v_cvt_pk_bf16_f32 v3, v6, v7
	v_cvt_pk_bf16_f32 v4, v14, v15
	v_cvt_pk_bf16_f32 v5, v12, v13
	global_store_dwordx4 v[16:17], v[2:5], off offset:256
	v_permlane32_swap_b32_e32 v0, v1
	v_add_f32_e32 v0, v0, v1
	s_and_saveexec_b64 s[4:5], s[6:7]
	s_cbranch_execz .LBB0_578
	v_lshlrev_b64 v[2:3], 6, v[88:89]
	v_lshl_add_u64 v[2:3], s[28:29], 0, v[2:3]
	v_lshl_add_u64 v[2:3], s[38:39], 2, v[2:3]
	s_lshl_b32 s12, s47, 2
	v_lshl_add_u64 v[2:3], v[2:3], 0, s[12:13]
	global_store_dword v[2:3], v0, off

.LBB0_969:
	v_lshl_or_b32 v168, s10, 8, v188
	v_lshl_add_u32 v172, s40, 8, v186
	v_ashrrev_i32_e32 v169, 31, v168
	v_lshlrev_b64 v[204:205], 1, v[168:169]
	v_ashrrev_i32_e32 v173, 31, v172
	v_lshl_add_u64 v[170:171], s[16:17], 0, v[204:205]
	v_lshlrev_b64 v[206:207], 11, v[172:173]
	v_lshl_add_u64 v[128:129], v[170:171], 0, v[206:207]
	global_load_dwordx4 v[192:195], v[128:129], off
	global_load_dwordx4 v[198:201], v[128:129], off offset:256
	v_or_b32_e32 v182, 16, v172
	v_or_b32_e32 v178, 32, v172
	v_or_b32_e32 v174, 48, v172
	v_ashrrev_i32_e32 v183, 31, v182
	v_ashrrev_i32_e32 v179, 31, v178
	v_ashrrev_i32_e32 v175, 31, v174
	v_lshlrev_b64 v[184:185], 11, v[182:183]
	v_lshlrev_b64 v[180:181], 11, v[178:179]
	v_lshlrev_b64 v[176:177], 11, v[174:175]
	v_lshl_add_u64 v[128:129], v[170:171], 0, v[184:185]
	v_lshl_add_u64 v[130:131], v[170:171], 0, v[180:181]
	v_lshl_add_u64 v[208:209], v[170:171], 0, v[176:177]
	global_load_dwordx4 v[148:151], v[128:129], off
	global_load_dwordx4 v[144:147], v[128:129], off offset:256
	global_load_dwordx4 v[140:143], v[130:131], off
	global_load_dwordx4 v[136:139], v[130:131], off offset:256
	global_load_dwordx4 v[132:135], v[208:209], off
	s_nop 0
	global_load_dwordx4 v[128:131], v[208:209], off offset:256
	v_add_u32_e32 v248, 0x80, v172
	v_ashrrev_i32_e32 v249, 31, v248
	v_lshlrev_b64 v[248:249], 11, v[248:249]
	v_lshl_add_u64 v[248:249], v[170:171], 0, v[248:249]
	global_load_dwordx4 v[216:219], v[248:249], off
	global_load_dwordx4 v[220:223], v[248:249], off offset:256
	v_add_u32_e32 v250, 0x90, v172
	v_ashrrev_i32_e32 v251, 31, v250
	v_lshlrev_b64 v[250:251], 11, v[250:251]
	v_lshl_add_u64 v[250:251], v[170:171], 0, v[250:251]
	global_load_dwordx4 v[224:227], v[250:251], off
	global_load_dwordx4 v[228:231], v[250:251], off offset:256
	v_add_u32_e32 v252, 0xa0, v172
	v_ashrrev_i32_e32 v253, 31, v252
	v_lshlrev_b64 v[252:253], 11, v[252:253]
	v_lshl_add_u64 v[252:253], v[170:171], 0, v[252:253]
	global_load_dwordx4 v[232:235], v[252:253], off
	global_load_dwordx4 v[236:239], v[252:253], off offset:256
	v_add_u32_e32 v248, 0xb0, v172
	v_ashrrev_i32_e32 v249, 31, v248
	v_lshlrev_b64 v[248:249], 11, v[248:249]
	v_lshl_add_u64 v[248:249], v[170:171], 0, v[248:249]
	global_load_dwordx4 v[240:243], v[248:249], off
	global_load_dwordx4 v[244:247], v[248:249], off offset:256
	s_lshl_b32 s40, s10, 2
	s_ashr_i32 s41, s40, 31
	s_waitcnt vmcnt(8)
	v_lshlrev_b32_e32 v208, 16, v192
	v_and_b32_e32 v209, 0xffff0000, v192
	v_lshlrev_b32_e32 v192, 16, v193
	v_and_b32_e32 v193, 0xffff0000, v193
	v_lshlrev_b32_e32 v210, 16, v194
	v_and_b32_e32 v211, 0xffff0000, v194
	v_lshlrev_b32_e32 v194, 16, v195
	v_and_b32_e32 v195, 0xffff0000, v195
	v_lshlrev_b32_e32 v212, 16, v198
	v_and_b32_e32 v213, 0xffff0000, v198
	v_lshlrev_b32_e32 v198, 16, v199
	v_and_b32_e32 v199, 0xffff0000, v199
	v_lshlrev_b32_e32 v214, 16, v200
	v_and_b32_e32 v215, 0xffff0000, v200
	v_lshlrev_b32_e32 v200, 16, v201
	v_and_b32_e32 v201, 0xffff0000, v201
	v_pk_add_f32 v[126:127], v[126:127], v[192:193]
	v_pk_add_f32 v[124:125], v[124:125], v[208:209]
	v_pk_add_f32 v[122:123], v[122:123], v[194:195]
	v_pk_add_f32 v[120:121], v[120:121], v[210:211]
	v_pk_add_f32 v[118:119], v[118:119], v[198:199]
	v_pk_add_f32 v[116:117], v[116:117], v[212:213]
	v_pk_add_f32 v[192:193], v[114:115], v[200:201]
	v_pk_add_f32 v[194:195], v[112:113], v[214:215]
	v_mul_f32_e32 v198, v125, v125
	v_mul_f32_e32 v199, v127, v127
	v_mul_f32_e32 v200, v121, v121
	v_mul_f32_e32 v201, v123, v123
	v_cvt_pk_bf16_f32 v112, v124, v125
	v_cvt_pk_bf16_f32 v113, v126, v127
	v_cvt_pk_bf16_f32 v114, v120, v121
	v_cvt_pk_bf16_f32 v115, v122, v123
	v_mul_f32_e32 v121, v117, v117
	v_mul_f32_e32 v123, v119, v119
	v_mul_f32_e32 v125, v195, v195
	v_mul_f32_e32 v127, v193, v193
	v_fmac_f32_e32 v198, v124, v124
	v_fmac_f32_e32 v199, v126, v126
	v_fmac_f32_e32 v200, v120, v120
	v_fmac_f32_e32 v201, v122, v122
	v_fmac_f32_e32 v121, v116, v116
	v_fmac_f32_e32 v123, v118, v118
	v_fmac_f32_e32 v125, v194, v194
	v_fmac_f32_e32 v127, v192, v192
	v_add_f32_e32 v120, v198, v199
	v_add_f32_e32 v122, v200, v201
	v_add_f32_e32 v121, v121, v123
	v_add_f32_e32 v123, v125, v127
	v_add_f32_e32 v120, v120, v122
	v_add_f32_e32 v121, v121, v123
	v_add_f32_e32 v122, v120, v121
	v_mov_b32_e32 v123, v122
	v_lshl_add_u64 v[120:121], s[16:17], 0, v[206:207]
	v_lshl_add_u64 v[120:121], v[120:121], 0, v[204:205]
	global_store_dwordx4 v[120:121], v[112:115], off
	s_waitcnt lgkmcnt(0)
	s_nop 0
	v_permlane16_swap_b32_e32 v122, v123
	v_add_f32_e32 v112, v122, v123
	v_mov_b32_e32 v113, v112
	v_cvt_pk_bf16_f32 v114, v116, v117
	v_cvt_pk_bf16_f32 v115, v118, v119
	v_cvt_pk_bf16_f32 v116, v194, v195
	v_cvt_pk_bf16_f32 v117, v192, v193
	global_store_dwordx4 v[120:121], v[114:117], off offset:256
	v_permlane32_swap_b32_e32 v112, v113
	v_add_f32_e32 v112, v112, v113
	s_and_saveexec_b64 s[4:5], s[6:7]
	s_cbranch_execz .LBB0_971
	v_lshlrev_b64 v[114:115], 6, v[172:173]
	v_lshl_add_u64 v[114:115], s[24:25], 0, v[114:115]
	v_lshl_add_u64 v[114:115], s[40:41], 2, v[114:115]
	s_lshl_b32 s10, s49, 2
	v_lshl_add_u64 v[114:115], v[114:115], 0, s[10:11]
	global_store_dword v[114:115], v112, off
.LBB0_971:
	s_or_b64 exec, exec, s[4:5]
	v_lshlrev_b32_e32 v112, 16, v148
	s_waitcnt lgkmcnt(0)
	v_and_b32_e32 v113, 0xffff0000, v148
	v_lshlrev_b32_e32 v114, 16, v149
	v_and_b32_e32 v115, 0xffff0000, v149
	v_lshlrev_b32_e32 v116, 16, v150
	v_and_b32_e32 v117, 0xffff0000, v150
	v_lshlrev_b32_e32 v118, 16, v151
	v_and_b32_e32 v119, 0xffff0000, v151
	v_pk_add_f32 v[110:111], v[110:111], v[114:115]
	v_pk_add_f32 v[108:109], v[108:109], v[112:113]
	v_pk_add_f32 v[112:113], v[106:107], v[118:119]
	v_pk_add_f32 v[106:107], v[104:105], v[116:117]
	v_mul_f32_e32 v104, v109, v109
	v_mul_f32_e32 v105, v111, v111
	v_fmac_f32_e32 v104, v108, v108
	v_fmac_f32_e32 v105, v110, v110
	v_add_f32_e32 v104, v104, v105
	v_mul_f32_e32 v105, v107, v107
	v_mul_f32_e32 v114, v113, v113
	v_fmac_f32_e32 v105, v106, v106
	v_fmac_f32_e32 v114, v112, v112
	v_add_f32_e32 v105, v105, v114
	v_add_f32_e32 v116, v104, v105
	v_cvt_pk_bf16_f32 v104, v108, v109
	v_cvt_pk_bf16_f32 v105, v110, v111
	v_lshlrev_b32_e32 v108, 16, v144
	v_and_b32_e32 v109, 0xffff0000, v144
	v_lshlrev_b32_e32 v110, 16, v145
	v_and_b32_e32 v111, 0xffff0000, v145
	v_cvt_pk_bf16_f32 v106, v106, v107
	v_cvt_pk_bf16_f32 v107, v112, v113
	v_lshlrev_b32_e32 v112, 16, v146
	v_and_b32_e32 v113, 0xffff0000, v146
	v_pk_add_f32 v[102:103], v[102:103], v[110:111]
	v_pk_add_f32 v[100:101], v[100:101], v[108:109]
	v_lshlrev_b32_e32 v114, 16, v147
	v_and_b32_e32 v115, 0xffff0000, v147
	v_pk_add_f32 v[110:111], v[96:97], v[112:113]
	v_mul_f32_e32 v96, v101, v101
	v_mul_f32_e32 v97, v103, v103
	v_pk_add_f32 v[108:109], v[98:99], v[114:115]
	v_fmac_f32_e32 v96, v100, v100
	v_fmac_f32_e32 v97, v102, v102
	v_add_f32_e32 v96, v96, v97
	v_mul_f32_e32 v97, v111, v111
	v_mul_f32_e32 v98, v109, v109
	v_fmac_f32_e32 v97, v110, v110
	v_fmac_f32_e32 v98, v108, v108
	v_add_f32_e32 v97, v97, v98
	v_add_f32_e32 v96, v96, v97
	v_add_f32_e32 v99, v116, v96
	v_mov_b32_e32 v114, v99
	v_lshl_add_u64 v[96:97], s[16:17], 0, v[184:185]
	v_lshl_add_u64 v[112:113], v[168:169], 1, v[96:97]
	global_store_dwordx4 v[112:113], v[104:107], off
	v_cvt_pk_bf16_f32 v98, v100, v101
	s_waitcnt lgkmcnt(0)
	v_permlane16_swap_b32_e32 v99, v114
	v_add_f32_e32 v96, v99, v114
	v_mov_b32_e32 v97, v96
	v_cvt_pk_bf16_f32 v99, v102, v103
	v_cvt_pk_bf16_f32 v100, v110, v111
	v_cvt_pk_bf16_f32 v101, v108, v109
	global_store_dwordx4 v[112:113], v[98:101], off offset:256
	v_permlane32_swap_b32_e32 v96, v97
	v_add_f32_e32 v96, v96, v97
	s_and_saveexec_b64 s[4:5], s[6:7]
	s_cbranch_execz .LBB0_973
	v_lshlrev_b64 v[98:99], 6, v[182:183]
	v_lshl_add_u64 v[98:99], s[24:25], 0, v[98:99]
	v_lshl_add_u64 v[98:99], s[40:41], 2, v[98:99]
	s_lshl_b32 s10, s49, 2
	v_lshl_add_u64 v[98:99], v[98:99], 0, s[10:11]
	global_store_dword v[98:99], v96, off
.LBB0_973:
	s_or_b64 exec, exec, s[4:5]
	v_lshlrev_b32_e32 v96, 16, v140
	s_waitcnt lgkmcnt(0)
	v_and_b32_e32 v97, 0xffff0000, v140
	v_lshlrev_b32_e32 v98, 16, v141
	v_and_b32_e32 v99, 0xffff0000, v141
	v_lshlrev_b32_e32 v100, 16, v142
	v_and_b32_e32 v101, 0xffff0000, v142
	v_lshlrev_b32_e32 v102, 16, v143
	v_and_b32_e32 v103, 0xffff0000, v143
	v_pk_add_f32 v[94:95], v[94:95], v[98:99]
	v_pk_add_f32 v[92:93], v[92:93], v[96:97]
	v_pk_add_f32 v[96:97], v[90:91], v[102:103]
	v_pk_add_f32 v[90:91], v[88:89], v[100:101]
	v_mul_f32_e32 v88, v93, v93
	v_mul_f32_e32 v89, v95, v95
	v_fmac_f32_e32 v88, v92, v92
	v_fmac_f32_e32 v89, v94, v94
	v_add_f32_e32 v88, v88, v89
	v_mul_f32_e32 v89, v91, v91
	v_mul_f32_e32 v98, v97, v97
	v_fmac_f32_e32 v89, v90, v90
	v_fmac_f32_e32 v98, v96, v96
	v_add_f32_e32 v89, v89, v98
	v_add_f32_e32 v100, v88, v89
	v_cvt_pk_bf16_f32 v88, v92, v93
	v_cvt_pk_bf16_f32 v89, v94, v95
	v_lshlrev_b32_e32 v92, 16, v136
	v_and_b32_e32 v93, 0xffff0000, v136
	v_lshlrev_b32_e32 v94, 16, v137
	v_and_b32_e32 v95, 0xffff0000, v137
	v_cvt_pk_bf16_f32 v90, v90, v91
	v_cvt_pk_bf16_f32 v91, v96, v97
	v_lshlrev_b32_e32 v96, 16, v138
	v_and_b32_e32 v97, 0xffff0000, v138
	v_pk_add_f32 v[86:87], v[86:87], v[94:95]
	v_pk_add_f32 v[84:85], v[84:85], v[92:93]
	v_lshlrev_b32_e32 v98, 16, v139
	v_and_b32_e32 v99, 0xffff0000, v139
	v_pk_add_f32 v[94:95], v[80:81], v[96:97]
	v_mul_f32_e32 v80, v85, v85
	v_mul_f32_e32 v81, v87, v87
	v_pk_add_f32 v[92:93], v[82:83], v[98:99]
	v_fmac_f32_e32 v80, v84, v84
	v_fmac_f32_e32 v81, v86, v86
	v_add_f32_e32 v80, v80, v81
	v_mul_f32_e32 v81, v95, v95
	v_mul_f32_e32 v82, v93, v93
	v_fmac_f32_e32 v81, v94, v94
	v_fmac_f32_e32 v82, v92, v92
	v_add_f32_e32 v81, v81, v82
	v_add_f32_e32 v80, v80, v81
	v_add_f32_e32 v83, v100, v80
	v_mov_b32_e32 v98, v83
	v_lshl_add_u64 v[80:81], s[16:17], 0, v[180:181]
	v_lshl_add_u64 v[96:97], v[168:169], 1, v[80:81]
	global_store_dwordx4 v[96:97], v[88:91], off
	v_cvt_pk_bf16_f32 v82, v84, v85
	s_waitcnt lgkmcnt(0)
	v_permlane16_swap_b32_e32 v83, v98
	v_add_f32_e32 v80, v83, v98
	v_mov_b32_e32 v81, v80
	v_cvt_pk_bf16_f32 v83, v86, v87
	v_cvt_pk_bf16_f32 v84, v94, v95
	v_cvt_pk_bf16_f32 v85, v92, v93
	global_store_dwordx4 v[96:97], v[82:85], off offset:256
	v_permlane32_swap_b32_e32 v80, v81
	v_add_f32_e32 v80, v80, v81
	s_and_saveexec_b64 s[4:5], s[6:7]
	s_cbranch_execz .LBB0_975
	v_lshlrev_b64 v[82:83], 6, v[178:179]
	v_lshl_add_u64 v[82:83], s[24:25], 0, v[82:83]
	v_lshl_add_u64 v[82:83], s[40:41], 2, v[82:83]
	s_lshl_b32 s10, s49, 2
	v_lshl_add_u64 v[82:83], v[82:83], 0, s[10:11]
	global_store_dword v[82:83], v80, off
.LBB0_975:
	s_or_b64 exec, exec, s[4:5]
	v_lshlrev_b32_e32 v80, 16, v132
	s_waitcnt lgkmcnt(0)
	v_and_b32_e32 v81, 0xffff0000, v132
	v_lshlrev_b32_e32 v82, 16, v133
	v_and_b32_e32 v83, 0xffff0000, v133
	v_lshlrev_b32_e32 v84, 16, v134
	v_and_b32_e32 v85, 0xffff0000, v134
	v_lshlrev_b32_e32 v86, 16, v135
	v_and_b32_e32 v87, 0xffff0000, v135
	v_pk_add_f32 v[78:79], v[78:79], v[82:83]
	v_pk_add_f32 v[76:77], v[76:77], v[80:81]
	v_pk_add_f32 v[80:81], v[74:75], v[86:87]
	v_pk_add_f32 v[74:75], v[72:73], v[84:85]
	v_mul_f32_e32 v72, v77, v77
	v_mul_f32_e32 v73, v79, v79
	v_fmac_f32_e32 v72, v76, v76
	v_fmac_f32_e32 v73, v78, v78
	v_add_f32_e32 v72, v72, v73
	v_mul_f32_e32 v73, v75, v75
	v_mul_f32_e32 v82, v81, v81
	v_fmac_f32_e32 v73, v74, v74
	v_fmac_f32_e32 v82, v80, v80
	v_add_f32_e32 v73, v73, v82
	v_add_f32_e32 v84, v72, v73
	v_cvt_pk_bf16_f32 v72, v76, v77
	v_cvt_pk_bf16_f32 v73, v78, v79
	v_lshlrev_b32_e32 v76, 16, v128
	v_and_b32_e32 v77, 0xffff0000, v128
	v_lshlrev_b32_e32 v78, 16, v129
	v_and_b32_e32 v79, 0xffff0000, v129
	v_cvt_pk_bf16_f32 v74, v74, v75
	v_cvt_pk_bf16_f32 v75, v80, v81
	v_lshlrev_b32_e32 v80, 16, v130
	v_and_b32_e32 v81, 0xffff0000, v130
	v_pk_add_f32 v[70:71], v[70:71], v[78:79]
	v_pk_add_f32 v[68:69], v[68:69], v[76:77]
	v_lshlrev_b32_e32 v82, 16, v131
	v_and_b32_e32 v83, 0xffff0000, v131
	v_pk_add_f32 v[78:79], v[64:65], v[80:81]
	v_mul_f32_e32 v64, v69, v69
	v_mul_f32_e32 v65, v71, v71
	v_pk_add_f32 v[76:77], v[66:67], v[82:83]
	v_fmac_f32_e32 v64, v68, v68
	v_fmac_f32_e32 v65, v70, v70
	v_add_f32_e32 v64, v64, v65
	v_mul_f32_e32 v65, v79, v79
	v_mul_f32_e32 v66, v77, v77
	v_fmac_f32_e32 v65, v78, v78
	v_fmac_f32_e32 v66, v76, v76
	v_add_f32_e32 v65, v65, v66
	v_add_f32_e32 v64, v64, v65
	v_add_f32_e32 v67, v84, v64
	v_mov_b32_e32 v82, v67
	v_lshl_add_u64 v[64:65], s[16:17], 0, v[176:177]
	v_lshl_add_u64 v[80:81], v[168:169], 1, v[64:65]
	global_store_dwordx4 v[80:81], v[72:75], off
	v_cvt_pk_bf16_f32 v66, v68, v69
	s_waitcnt lgkmcnt(0)
	v_permlane16_swap_b32_e32 v67, v82
	v_add_f32_e32 v64, v67, v82
	v_mov_b32_e32 v65, v64
	v_cvt_pk_bf16_f32 v67, v70, v71
	v_cvt_pk_bf16_f32 v68, v78, v79
	v_cvt_pk_bf16_f32 v69, v76, v77
	global_store_dwordx4 v[80:81], v[66:69], off offset:256
	v_permlane32_swap_b32_e32 v64, v65
	v_add_f32_e32 v64, v64, v65
	s_and_saveexec_b64 s[4:5], s[6:7]
	s_cbranch_execz .LBB0_977
	v_lshlrev_b64 v[66:67], 6, v[174:175]
	v_lshl_add_u64 v[66:67], s[24:25], 0, v[66:67]
	v_lshl_add_u64 v[66:67], s[40:41], 2, v[66:67]
	s_lshl_b32 s10, s49, 2
	v_lshl_add_u64 v[66:67], v[66:67], 0, s[10:11]
	global_store_dword v[66:67], v64, off
.LBB0_977:
	s_or_b64 exec, exec, s[4:5]
	v_add_u32_e32 v100, 0x80, v172
	v_ashrrev_i32_e32 v101, 31, v100
	v_lshlrev_b64 v[110:111], 11, v[100:101]
	s_waitcnt lgkmcnt(0)
	v_lshl_add_u64 v[64:65], v[170:171], 0, v[110:111]
	v_add_u32_e32 v96, 0x90, v172
	v_add_u32_e32 v92, 0xa0, v172
	v_add_u32_e32 v88, 0xb0, v172
	v_ashrrev_i32_e32 v97, 31, v96
	v_ashrrev_i32_e32 v93, 31, v92
	v_ashrrev_i32_e32 v89, 31, v88
	v_lshlrev_b64 v[98:99], 11, v[96:97]
	v_lshlrev_b64 v[94:95], 11, v[92:93]
	v_lshlrev_b64 v[90:91], 11, v[88:89]
	v_lshl_add_u64 v[64:65], v[170:171], 0, v[98:99]
	v_lshl_add_u64 v[66:67], v[170:171], 0, v[94:95]
	v_lshl_add_u64 v[112:113], v[170:171], 0, v[90:91]
	s_waitcnt vmcnt(15)
	v_lshlrev_b32_e32 v112, 16, v216
	v_and_b32_e32 v113, 0xffff0000, v216
	v_lshlrev_b32_e32 v102, 16, v217
	v_and_b32_e32 v103, 0xffff0000, v217
	v_lshlrev_b32_e32 v114, 16, v218
	v_and_b32_e32 v115, 0xffff0000, v218
	v_lshlrev_b32_e32 v104, 16, v219
	v_and_b32_e32 v105, 0xffff0000, v219
	s_waitcnt vmcnt(14)
	v_lshlrev_b32_e32 v116, 16, v220
	v_and_b32_e32 v117, 0xffff0000, v220
	v_lshlrev_b32_e32 v106, 16, v221
	v_and_b32_e32 v107, 0xffff0000, v221
	v_lshlrev_b32_e32 v118, 16, v222
	v_and_b32_e32 v119, 0xffff0000, v222
	v_lshlrev_b32_e32 v108, 16, v223
	v_and_b32_e32 v109, 0xffff0000, v223
	v_pk_add_f32 v[62:63], v[62:63], v[102:103]
	v_pk_add_f32 v[60:61], v[60:61], v[112:113]
	v_pk_add_f32 v[58:59], v[58:59], v[104:105]
	v_pk_add_f32 v[56:57], v[56:57], v[114:115]
	v_pk_add_f32 v[54:55], v[54:55], v[106:107]
	v_pk_add_f32 v[52:53], v[52:53], v[116:117]
	v_pk_add_f32 v[102:103], v[50:51], v[108:109]
	v_pk_add_f32 v[104:105], v[48:49], v[118:119]
	v_mul_f32_e32 v106, v61, v61
	v_mul_f32_e32 v107, v63, v63
	v_mul_f32_e32 v108, v57, v57
	v_mul_f32_e32 v109, v59, v59
	v_cvt_pk_bf16_f32 v48, v60, v61
	v_cvt_pk_bf16_f32 v49, v62, v63
	v_cvt_pk_bf16_f32 v50, v56, v57
	v_cvt_pk_bf16_f32 v51, v58, v59
	v_mul_f32_e32 v57, v53, v53
	v_mul_f32_e32 v59, v55, v55
	v_mul_f32_e32 v61, v105, v105
	v_mul_f32_e32 v63, v103, v103
	v_fmac_f32_e32 v106, v60, v60
	v_fmac_f32_e32 v107, v62, v62
	v_fmac_f32_e32 v108, v56, v56
	v_fmac_f32_e32 v109, v58, v58
	v_fmac_f32_e32 v57, v52, v52
	v_fmac_f32_e32 v59, v54, v54
	v_fmac_f32_e32 v61, v104, v104
	v_fmac_f32_e32 v63, v102, v102
	v_add_f32_e32 v56, v106, v107
	v_add_f32_e32 v58, v108, v109
	v_add_f32_e32 v57, v57, v59
	v_add_f32_e32 v59, v61, v63
	v_add_f32_e32 v56, v56, v58
	v_add_f32_e32 v57, v57, v59
	v_add_f32_e32 v58, v56, v57
	v_mov_b32_e32 v59, v58
	v_lshl_add_u64 v[56:57], s[16:17], 0, v[110:111]
	v_lshl_add_u64 v[56:57], v[168:169], 1, v[56:57]
	global_store_dwordx4 v[56:57], v[48:51], off
	s_waitcnt lgkmcnt(0)
	s_nop 0
	v_permlane16_swap_b32_e32 v58, v59
	v_add_f32_e32 v48, v58, v59
	v_mov_b32_e32 v49, v48
	v_cvt_pk_bf16_f32 v50, v52, v53
	v_cvt_pk_bf16_f32 v51, v54, v55
	v_cvt_pk_bf16_f32 v52, v104, v105
	v_cvt_pk_bf16_f32 v53, v102, v103
	global_store_dwordx4 v[56:57], v[50:53], off offset:256
	v_permlane32_swap_b32_e32 v48, v49
	v_add_f32_e32 v48, v48, v49
	s_and_saveexec_b64 s[4:5], s[6:7]
	s_cbranch_execz .LBB0_979
	v_lshlrev_b64 v[50:51], 6, v[100:101]
	v_lshl_add_u64 v[50:51], s[24:25], 0, v[50:51]
	v_lshl_add_u64 v[50:51], s[40:41], 2, v[50:51]
	s_lshl_b32 s10, s49, 2
	v_lshl_add_u64 v[50:51], v[50:51], 0, s[10:11]
	global_store_dword v[50:51], v48, off
.LBB0_979:
	s_or_b64 exec, exec, s[4:5]
	s_waitcnt vmcnt(15)
	v_lshlrev_b32_e32 v48, 16, v224
	s_waitcnt lgkmcnt(0)
	v_and_b32_e32 v49, 0xffff0000, v224
	v_lshlrev_b32_e32 v50, 16, v225
	v_and_b32_e32 v51, 0xffff0000, v225
	v_lshlrev_b32_e32 v52, 16, v226
	v_and_b32_e32 v53, 0xffff0000, v226
	v_lshlrev_b32_e32 v54, 16, v227
	v_and_b32_e32 v55, 0xffff0000, v227
	v_pk_add_f32 v[46:47], v[46:47], v[50:51]
	v_pk_add_f32 v[44:45], v[44:45], v[48:49]
	v_pk_add_f32 v[48:49], v[42:43], v[54:55]
	v_pk_add_f32 v[42:43], v[40:41], v[52:53]
	v_mul_f32_e32 v40, v45, v45
	v_mul_f32_e32 v41, v47, v47
	v_fmac_f32_e32 v40, v44, v44
	v_fmac_f32_e32 v41, v46, v46
	v_add_f32_e32 v40, v40, v41
	v_mul_f32_e32 v41, v43, v43
	v_mul_f32_e32 v50, v49, v49
	v_fmac_f32_e32 v41, v42, v42
	v_fmac_f32_e32 v50, v48, v48
	v_add_f32_e32 v41, v41, v50
	v_add_f32_e32 v52, v40, v41
	v_cvt_pk_bf16_f32 v40, v44, v45
	v_cvt_pk_bf16_f32 v41, v46, v47
	s_waitcnt vmcnt(14)
	v_lshlrev_b32_e32 v44, 16, v228
	v_and_b32_e32 v45, 0xffff0000, v228
	v_lshlrev_b32_e32 v46, 16, v229
	v_and_b32_e32 v47, 0xffff0000, v229
	v_cvt_pk_bf16_f32 v42, v42, v43
	v_cvt_pk_bf16_f32 v43, v48, v49
	v_lshlrev_b32_e32 v48, 16, v230
	v_and_b32_e32 v49, 0xffff0000, v230
	v_pk_add_f32 v[38:39], v[38:39], v[46:47]
	v_pk_add_f32 v[36:37], v[36:37], v[44:45]
	v_lshlrev_b32_e32 v50, 16, v231
	v_and_b32_e32 v51, 0xffff0000, v231
	v_pk_add_f32 v[46:47], v[32:33], v[48:49]
	v_mul_f32_e32 v32, v37, v37
	v_mul_f32_e32 v33, v39, v39
	v_pk_add_f32 v[44:45], v[34:35], v[50:51]
	v_fmac_f32_e32 v32, v36, v36
	v_fmac_f32_e32 v33, v38, v38
	v_add_f32_e32 v32, v32, v33
	v_mul_f32_e32 v33, v47, v47
	v_mul_f32_e32 v34, v45, v45
	v_fmac_f32_e32 v33, v46, v46
	v_fmac_f32_e32 v34, v44, v44
	v_add_f32_e32 v33, v33, v34
	v_add_f32_e32 v32, v32, v33
	v_add_f32_e32 v35, v52, v32
	v_mov_b32_e32 v50, v35
	v_lshl_add_u64 v[32:33], s[16:17], 0, v[98:99]
	v_lshl_add_u64 v[48:49], v[168:169], 1, v[32:33]
	global_store_dwordx4 v[48:49], v[40:43], off
	v_cvt_pk_bf16_f32 v34, v36, v37
	s_waitcnt lgkmcnt(0)
	v_permlane16_swap_b32_e32 v35, v50
	v_add_f32_e32 v32, v35, v50
	v_mov_b32_e32 v33, v32
	v_cvt_pk_bf16_f32 v35, v38, v39
	v_cvt_pk_bf16_f32 v36, v46, v47
	v_cvt_pk_bf16_f32 v37, v44, v45
	global_store_dwordx4 v[48:49], v[34:37], off offset:256
	v_permlane32_swap_b32_e32 v32, v33
	v_add_f32_e32 v32, v32, v33
	s_and_saveexec_b64 s[4:5], s[6:7]
	s_cbranch_execz .LBB0_981
	v_lshlrev_b64 v[34:35], 6, v[96:97]
	v_lshl_add_u64 v[34:35], s[24:25], 0, v[34:35]
	v_lshl_add_u64 v[34:35], s[40:41], 2, v[34:35]
	s_lshl_b32 s10, s49, 2
	v_lshl_add_u64 v[34:35], v[34:35], 0, s[10:11]
	global_store_dword v[34:35], v32, off
.LBB0_981:
	s_or_b64 exec, exec, s[4:5]
	s_waitcnt vmcnt(15)
	v_lshlrev_b32_e32 v32, 16, v232
	s_waitcnt lgkmcnt(0)
	v_and_b32_e32 v33, 0xffff0000, v232
	v_lshlrev_b32_e32 v34, 16, v233
	v_and_b32_e32 v35, 0xffff0000, v233
	v_lshlrev_b32_e32 v36, 16, v234
	v_and_b32_e32 v37, 0xffff0000, v234
	v_lshlrev_b32_e32 v38, 16, v235
	v_and_b32_e32 v39, 0xffff0000, v235
	v_pk_add_f32 v[30:31], v[30:31], v[34:35]
	v_pk_add_f32 v[28:29], v[28:29], v[32:33]
	v_pk_add_f32 v[32:33], v[26:27], v[38:39]
	v_pk_add_f32 v[26:27], v[24:25], v[36:37]
	v_mul_f32_e32 v24, v29, v29
	v_mul_f32_e32 v25, v31, v31
	v_fmac_f32_e32 v24, v28, v28
	v_fmac_f32_e32 v25, v30, v30
	v_add_f32_e32 v24, v24, v25
	v_mul_f32_e32 v25, v27, v27
	v_mul_f32_e32 v34, v33, v33
	v_fmac_f32_e32 v25, v26, v26
	v_fmac_f32_e32 v34, v32, v32
	v_add_f32_e32 v25, v25, v34
	v_add_f32_e32 v36, v24, v25
	v_cvt_pk_bf16_f32 v24, v28, v29
	v_cvt_pk_bf16_f32 v25, v30, v31
	s_waitcnt vmcnt(14)
	v_lshlrev_b32_e32 v28, 16, v236
	v_and_b32_e32 v29, 0xffff0000, v236
	v_lshlrev_b32_e32 v30, 16, v237
	v_and_b32_e32 v31, 0xffff0000, v237
	v_cvt_pk_bf16_f32 v26, v26, v27
	v_cvt_pk_bf16_f32 v27, v32, v33
	v_lshlrev_b32_e32 v32, 16, v238
	v_and_b32_e32 v33, 0xffff0000, v238
	v_pk_add_f32 v[22:23], v[22:23], v[30:31]
	v_pk_add_f32 v[20:21], v[20:21], v[28:29]
	v_lshlrev_b32_e32 v34, 16, v239
	v_and_b32_e32 v35, 0xffff0000, v239
	v_pk_add_f32 v[30:31], v[16:17], v[32:33]
	v_mul_f32_e32 v16, v21, v21
	v_mul_f32_e32 v17, v23, v23
	v_pk_add_f32 v[28:29], v[18:19], v[34:35]
	v_fmac_f32_e32 v16, v20, v20
	v_fmac_f32_e32 v17, v22, v22
	v_add_f32_e32 v16, v16, v17
	v_mul_f32_e32 v17, v31, v31
	v_mul_f32_e32 v18, v29, v29
	v_fmac_f32_e32 v17, v30, v30
	v_fmac_f32_e32 v18, v28, v28
	v_add_f32_e32 v17, v17, v18
	v_add_f32_e32 v16, v16, v17
	v_add_f32_e32 v19, v36, v16
	v_mov_b32_e32 v34, v19
	v_lshl_add_u64 v[16:17], s[16:17], 0, v[94:95]
	v_lshl_add_u64 v[32:33], v[168:169], 1, v[16:17]
	global_store_dwordx4 v[32:33], v[24:27], off
	v_cvt_pk_bf16_f32 v18, v20, v21
	s_waitcnt lgkmcnt(0)
	v_permlane16_swap_b32_e32 v19, v34
	v_add_f32_e32 v16, v19, v34
	v_mov_b32_e32 v17, v16
	v_cvt_pk_bf16_f32 v19, v22, v23
	v_cvt_pk_bf16_f32 v20, v30, v31
	v_cvt_pk_bf16_f32 v21, v28, v29
	global_store_dwordx4 v[32:33], v[18:21], off offset:256
	v_permlane32_swap_b32_e32 v16, v17
	v_add_f32_e32 v16, v16, v17
	s_and_saveexec_b64 s[4:5], s[6:7]
	s_cbranch_execz .LBB0_983
	v_lshlrev_b64 v[18:19], 6, v[92:93]
	v_lshl_add_u64 v[18:19], s[24:25], 0, v[18:19]
	v_lshl_add_u64 v[18:19], s[40:41], 2, v[18:19]
	s_lshl_b32 s10, s49, 2
	v_lshl_add_u64 v[18:19], v[18:19], 0, s[10:11]
	global_store_dword v[18:19], v16, off
.LBB0_983:
	s_or_b64 exec, exec, s[4:5]
	s_waitcnt vmcnt(15)
	v_lshlrev_b32_e32 v16, 16, v240
	s_waitcnt lgkmcnt(0)
	v_and_b32_e32 v17, 0xffff0000, v240
	v_lshlrev_b32_e32 v18, 16, v241
	v_and_b32_e32 v19, 0xffff0000, v241
	v_lshlrev_b32_e32 v20, 16, v242
	v_and_b32_e32 v21, 0xffff0000, v242
	v_lshlrev_b32_e32 v22, 16, v243
	v_and_b32_e32 v23, 0xffff0000, v243
	v_pk_add_f32 v[14:15], v[14:15], v[18:19]
	v_pk_add_f32 v[12:13], v[12:13], v[16:17]
	v_pk_add_f32 v[16:17], v[10:11], v[22:23]
	v_pk_add_f32 v[10:11], v[8:9], v[20:21]
	v_mul_f32_e32 v8, v13, v13
	v_mul_f32_e32 v9, v15, v15
	v_fmac_f32_e32 v8, v12, v12
	v_fmac_f32_e32 v9, v14, v14
	v_add_f32_e32 v8, v8, v9
	v_mul_f32_e32 v9, v11, v11
	v_mul_f32_e32 v18, v17, v17
	v_fmac_f32_e32 v9, v10, v10
	v_fmac_f32_e32 v18, v16, v16
	v_add_f32_e32 v9, v9, v18
	v_add_f32_e32 v20, v8, v9
	v_cvt_pk_bf16_f32 v8, v12, v13
	v_cvt_pk_bf16_f32 v9, v14, v15
	s_waitcnt vmcnt(14)
	v_lshlrev_b32_e32 v12, 16, v244
	v_and_b32_e32 v13, 0xffff0000, v244
	v_lshlrev_b32_e32 v14, 16, v245
	v_and_b32_e32 v15, 0xffff0000, v245
	v_cvt_pk_bf16_f32 v10, v10, v11
	v_cvt_pk_bf16_f32 v11, v16, v17
	v_lshlrev_b32_e32 v16, 16, v246
	v_and_b32_e32 v17, 0xffff0000, v246
	v_pk_add_f32 v[6:7], v[6:7], v[14:15]
	v_pk_add_f32 v[4:5], v[4:5], v[12:13]
	v_lshlrev_b32_e32 v18, 16, v247
	v_and_b32_e32 v19, 0xffff0000, v247
	v_pk_add_f32 v[14:15], v[0:1], v[16:17]
	v_mul_f32_e32 v0, v5, v5
	v_mul_f32_e32 v1, v7, v7
	v_pk_add_f32 v[12:13], v[2:3], v[18:19]
	v_fmac_f32_e32 v0, v4, v4
	v_fmac_f32_e32 v1, v6, v6
	v_add_f32_e32 v0, v0, v1
	v_mul_f32_e32 v1, v15, v15
	v_mul_f32_e32 v2, v13, v13
	v_fmac_f32_e32 v1, v14, v14
	v_fmac_f32_e32 v2, v12, v12
	v_add_f32_e32 v1, v1, v2
	v_add_f32_e32 v0, v0, v1
	v_add_f32_e32 v3, v20, v0
	v_mov_b32_e32 v18, v3
	v_lshl_add_u64 v[0:1], s[16:17], 0, v[90:91]
	v_lshl_add_u64 v[16:17], v[168:169], 1, v[0:1]
	global_store_dwordx4 v[16:17], v[8:11], off
	v_cvt_pk_bf16_f32 v2, v4, v5
	s_waitcnt lgkmcnt(0)
	v_permlane16_swap_b32_e32 v3, v18
	v_add_f32_e32 v0, v3, v18
	v_mov_b32_e32 v1, v0
	v_cvt_pk_bf16_f32 v3, v6, v7
	v_cvt_pk_bf16_f32 v4, v14, v15
	v_cvt_pk_bf16_f32 v5, v12, v13
	global_store_dwordx4 v[16:17], v[2:5], off offset:256
	v_permlane32_swap_b32_e32 v0, v1
	v_add_f32_e32 v0, v0, v1
	s_and_saveexec_b64 s[4:5], s[6:7]
	s_cbranch_execz .LBB0_985
	v_lshlrev_b64 v[2:3], 6, v[88:89]
	v_lshl_add_u64 v[2:3], s[24:25], 0, v[2:3]
	v_lshl_add_u64 v[2:3], s[40:41], 2, v[2:3]
	s_lshl_b32 s10, s49, 2
	v_lshl_add_u64 v[2:3], v[2:3], 0, s[10:11]
	global_store_dword v[2:3], v0, off

.LBB0_1127:
	v_lshl_or_b32 v168, s10, 8, v188
	v_lshl_add_u32 v172, s53, 8, v186
	v_ashrrev_i32_e32 v169, 31, v168
	v_lshlrev_b64 v[204:205], 1, v[168:169]
	v_ashrrev_i32_e32 v173, 31, v172
	v_lshl_add_u64 v[170:171], s[16:17], 0, v[204:205]
	v_lshlrev_b64 v[206:207], 11, v[172:173]
	v_lshl_add_u64 v[128:129], v[170:171], 0, v[206:207]
	global_load_dwordx4 v[192:195], v[128:129], off
	global_load_dwordx4 v[198:201], v[128:129], off offset:256
	v_or_b32_e32 v182, 16, v172
	v_or_b32_e32 v178, 32, v172
	v_or_b32_e32 v174, 48, v172
	v_ashrrev_i32_e32 v183, 31, v182
	v_ashrrev_i32_e32 v179, 31, v178
	v_ashrrev_i32_e32 v175, 31, v174
	v_lshlrev_b64 v[184:185], 11, v[182:183]
	v_lshlrev_b64 v[180:181], 11, v[178:179]
	v_lshlrev_b64 v[176:177], 11, v[174:175]
	v_lshl_add_u64 v[128:129], v[170:171], 0, v[184:185]
	v_lshl_add_u64 v[130:131], v[170:171], 0, v[180:181]
	v_lshl_add_u64 v[208:209], v[170:171], 0, v[176:177]
	global_load_dwordx4 v[148:151], v[128:129], off
	global_load_dwordx4 v[144:147], v[128:129], off offset:256
	global_load_dwordx4 v[140:143], v[130:131], off
	global_load_dwordx4 v[136:139], v[130:131], off offset:256
	global_load_dwordx4 v[132:135], v[208:209], off
	s_nop 0
	global_load_dwordx4 v[128:131], v[208:209], off offset:256
	v_add_u32_e32 v248, 0x80, v172
	v_ashrrev_i32_e32 v249, 31, v248
	v_lshlrev_b64 v[248:249], 11, v[248:249]
	v_lshl_add_u64 v[248:249], v[170:171], 0, v[248:249]
	global_load_dwordx4 v[216:219], v[248:249], off
	global_load_dwordx4 v[220:223], v[248:249], off offset:256
	v_add_u32_e32 v250, 0x90, v172
	v_ashrrev_i32_e32 v251, 31, v250
	v_lshlrev_b64 v[250:251], 11, v[250:251]
	v_lshl_add_u64 v[250:251], v[170:171], 0, v[250:251]
	global_load_dwordx4 v[224:227], v[250:251], off
	global_load_dwordx4 v[228:231], v[250:251], off offset:256
	v_add_u32_e32 v252, 0xa0, v172
	v_ashrrev_i32_e32 v253, 31, v252
	v_lshlrev_b64 v[252:253], 11, v[252:253]
	v_lshl_add_u64 v[252:253], v[170:171], 0, v[252:253]
	global_load_dwordx4 v[232:235], v[252:253], off
	global_load_dwordx4 v[236:239], v[252:253], off offset:256
	v_add_u32_e32 v248, 0xb0, v172
	v_ashrrev_i32_e32 v249, 31, v248
	v_lshlrev_b64 v[248:249], 11, v[248:249]
	v_lshl_add_u64 v[248:249], v[170:171], 0, v[248:249]
	global_load_dwordx4 v[240:243], v[248:249], off
	global_load_dwordx4 v[244:247], v[248:249], off offset:256
	s_lshl_b32 s30, s10, 2
	s_ashr_i32 s31, s30, 31
	s_waitcnt vmcnt(8)
	v_lshlrev_b32_e32 v208, 16, v192
	v_and_b32_e32 v209, 0xffff0000, v192
	v_lshlrev_b32_e32 v192, 16, v193
	v_and_b32_e32 v193, 0xffff0000, v193
	v_lshlrev_b32_e32 v210, 16, v194
	v_and_b32_e32 v211, 0xffff0000, v194
	v_lshlrev_b32_e32 v194, 16, v195
	v_and_b32_e32 v195, 0xffff0000, v195
	v_lshlrev_b32_e32 v212, 16, v198
	v_and_b32_e32 v213, 0xffff0000, v198
	v_lshlrev_b32_e32 v198, 16, v199
	v_and_b32_e32 v199, 0xffff0000, v199
	v_lshlrev_b32_e32 v214, 16, v200
	v_and_b32_e32 v215, 0xffff0000, v200
	v_lshlrev_b32_e32 v200, 16, v201
	v_and_b32_e32 v201, 0xffff0000, v201
	v_pk_add_f32 v[126:127], v[126:127], v[192:193]
	v_pk_add_f32 v[124:125], v[124:125], v[208:209]
	v_pk_add_f32 v[122:123], v[122:123], v[194:195]
	v_pk_add_f32 v[120:121], v[120:121], v[210:211]
	v_pk_add_f32 v[118:119], v[118:119], v[198:199]
	v_pk_add_f32 v[116:117], v[116:117], v[212:213]
	v_pk_add_f32 v[192:193], v[114:115], v[200:201]
	v_pk_add_f32 v[194:195], v[112:113], v[214:215]
	v_mul_f32_e32 v198, v125, v125
	v_mul_f32_e32 v199, v127, v127
	v_mul_f32_e32 v200, v121, v121
	v_mul_f32_e32 v201, v123, v123
	v_cvt_pk_bf16_f32 v112, v124, v125
	v_cvt_pk_bf16_f32 v113, v126, v127
	v_cvt_pk_bf16_f32 v114, v120, v121
	v_cvt_pk_bf16_f32 v115, v122, v123
	v_mul_f32_e32 v121, v117, v117
	v_mul_f32_e32 v123, v119, v119
	v_mul_f32_e32 v125, v195, v195
	v_mul_f32_e32 v127, v193, v193
	v_fmac_f32_e32 v198, v124, v124
	v_fmac_f32_e32 v199, v126, v126
	v_fmac_f32_e32 v200, v120, v120
	v_fmac_f32_e32 v201, v122, v122
	v_fmac_f32_e32 v121, v116, v116
	v_fmac_f32_e32 v123, v118, v118
	v_fmac_f32_e32 v125, v194, v194
	v_fmac_f32_e32 v127, v192, v192
	v_add_f32_e32 v120, v198, v199
	v_add_f32_e32 v122, v200, v201
	v_add_f32_e32 v121, v121, v123
	v_add_f32_e32 v123, v125, v127
	v_add_f32_e32 v120, v120, v122
	v_add_f32_e32 v121, v121, v123
	v_add_f32_e32 v122, v120, v121
	v_mov_b32_e32 v123, v122
	v_lshl_add_u64 v[120:121], s[16:17], 0, v[206:207]
	v_lshl_add_u64 v[120:121], v[120:121], 0, v[204:205]
	global_store_dwordx4 v[120:121], v[112:115], off
	s_waitcnt lgkmcnt(0)
	s_nop 0
	v_permlane16_swap_b32_e32 v122, v123
	v_add_f32_e32 v112, v122, v123
	v_mov_b32_e32 v113, v112
	v_cvt_pk_bf16_f32 v114, v116, v117
	v_cvt_pk_bf16_f32 v115, v118, v119
	v_cvt_pk_bf16_f32 v116, v194, v195
	v_cvt_pk_bf16_f32 v117, v192, v193
	global_store_dwordx4 v[120:121], v[114:117], off offset:256
	v_permlane32_swap_b32_e32 v112, v113
	v_add_f32_e32 v112, v112, v113
	s_and_saveexec_b64 s[34:35], s[4:5]
	s_cbranch_execz .LBB0_1129
	v_lshlrev_b64 v[114:115], 6, v[172:173]
	v_lshl_add_u64 v[114:115], s[22:23], 0, v[114:115]
	v_lshl_add_u64 v[114:115], s[30:31], 2, v[114:115]
	s_lshl_b32 s10, s45, 2
	v_lshl_add_u64 v[114:115], v[114:115], 0, s[10:11]
	global_store_dword v[114:115], v112, off
.LBB0_1129:
	s_or_b64 exec, exec, s[34:35]
	v_lshlrev_b32_e32 v112, 16, v148
	s_waitcnt lgkmcnt(0)
	v_and_b32_e32 v113, 0xffff0000, v148
	v_lshlrev_b32_e32 v114, 16, v149
	v_and_b32_e32 v115, 0xffff0000, v149
	v_lshlrev_b32_e32 v116, 16, v150
	v_and_b32_e32 v117, 0xffff0000, v150
	v_lshlrev_b32_e32 v118, 16, v151
	v_and_b32_e32 v119, 0xffff0000, v151
	v_pk_add_f32 v[110:111], v[110:111], v[114:115]
	v_pk_add_f32 v[108:109], v[108:109], v[112:113]
	v_pk_add_f32 v[112:113], v[106:107], v[118:119]
	v_pk_add_f32 v[106:107], v[104:105], v[116:117]
	v_mul_f32_e32 v104, v109, v109
	v_mul_f32_e32 v105, v111, v111
	v_fmac_f32_e32 v104, v108, v108
	v_fmac_f32_e32 v105, v110, v110
	v_add_f32_e32 v104, v104, v105
	v_mul_f32_e32 v105, v107, v107
	v_mul_f32_e32 v114, v113, v113
	v_fmac_f32_e32 v105, v106, v106
	v_fmac_f32_e32 v114, v112, v112
	v_add_f32_e32 v105, v105, v114
	v_add_f32_e32 v116, v104, v105
	v_cvt_pk_bf16_f32 v104, v108, v109
	v_cvt_pk_bf16_f32 v105, v110, v111
	v_lshlrev_b32_e32 v108, 16, v144
	v_and_b32_e32 v109, 0xffff0000, v144
	v_lshlrev_b32_e32 v110, 16, v145
	v_and_b32_e32 v111, 0xffff0000, v145
	v_cvt_pk_bf16_f32 v106, v106, v107
	v_cvt_pk_bf16_f32 v107, v112, v113
	v_lshlrev_b32_e32 v112, 16, v146
	v_and_b32_e32 v113, 0xffff0000, v146
	v_pk_add_f32 v[102:103], v[102:103], v[110:111]
	v_pk_add_f32 v[100:101], v[100:101], v[108:109]
	v_lshlrev_b32_e32 v114, 16, v147
	v_and_b32_e32 v115, 0xffff0000, v147
	v_pk_add_f32 v[110:111], v[96:97], v[112:113]
	v_mul_f32_e32 v96, v101, v101
	v_mul_f32_e32 v97, v103, v103
	v_pk_add_f32 v[108:109], v[98:99], v[114:115]
	v_fmac_f32_e32 v96, v100, v100
	v_fmac_f32_e32 v97, v102, v102
	v_add_f32_e32 v96, v96, v97
	v_mul_f32_e32 v97, v111, v111
	v_mul_f32_e32 v98, v109, v109
	v_fmac_f32_e32 v97, v110, v110
	v_fmac_f32_e32 v98, v108, v108
	v_add_f32_e32 v97, v97, v98
	v_add_f32_e32 v96, v96, v97
	v_add_f32_e32 v99, v116, v96
	v_mov_b32_e32 v114, v99
	v_lshl_add_u64 v[96:97], s[16:17], 0, v[184:185]
	v_lshl_add_u64 v[112:113], v[168:169], 1, v[96:97]
	global_store_dwordx4 v[112:113], v[104:107], off
	v_cvt_pk_bf16_f32 v98, v100, v101
	s_waitcnt lgkmcnt(0)
	v_permlane16_swap_b32_e32 v99, v114
	v_add_f32_e32 v96, v99, v114
	v_mov_b32_e32 v97, v96
	v_cvt_pk_bf16_f32 v99, v102, v103
	v_cvt_pk_bf16_f32 v100, v110, v111
	v_cvt_pk_bf16_f32 v101, v108, v109
	global_store_dwordx4 v[112:113], v[98:101], off offset:256
	v_permlane32_swap_b32_e32 v96, v97
	v_add_f32_e32 v96, v96, v97
	s_and_saveexec_b64 s[34:35], s[4:5]
	s_cbranch_execz .LBB0_1131
	v_lshlrev_b64 v[98:99], 6, v[182:183]
	v_lshl_add_u64 v[98:99], s[22:23], 0, v[98:99]
	v_lshl_add_u64 v[98:99], s[30:31], 2, v[98:99]
	s_lshl_b32 s10, s45, 2
	v_lshl_add_u64 v[98:99], v[98:99], 0, s[10:11]
	global_store_dword v[98:99], v96, off
.LBB0_1131:
	s_or_b64 exec, exec, s[34:35]
	v_lshlrev_b32_e32 v96, 16, v140
	s_waitcnt lgkmcnt(0)
	v_and_b32_e32 v97, 0xffff0000, v140
	v_lshlrev_b32_e32 v98, 16, v141
	v_and_b32_e32 v99, 0xffff0000, v141
	v_lshlrev_b32_e32 v100, 16, v142
	v_and_b32_e32 v101, 0xffff0000, v142
	v_lshlrev_b32_e32 v102, 16, v143
	v_and_b32_e32 v103, 0xffff0000, v143
	v_pk_add_f32 v[94:95], v[94:95], v[98:99]
	v_pk_add_f32 v[92:93], v[92:93], v[96:97]
	v_pk_add_f32 v[96:97], v[90:91], v[102:103]
	v_pk_add_f32 v[90:91], v[88:89], v[100:101]
	v_mul_f32_e32 v88, v93, v93
	v_mul_f32_e32 v89, v95, v95
	v_fmac_f32_e32 v88, v92, v92
	v_fmac_f32_e32 v89, v94, v94
	v_add_f32_e32 v88, v88, v89
	v_mul_f32_e32 v89, v91, v91
	v_mul_f32_e32 v98, v97, v97
	v_fmac_f32_e32 v89, v90, v90
	v_fmac_f32_e32 v98, v96, v96
	v_add_f32_e32 v89, v89, v98
	v_add_f32_e32 v100, v88, v89
	v_cvt_pk_bf16_f32 v88, v92, v93
	v_cvt_pk_bf16_f32 v89, v94, v95
	v_lshlrev_b32_e32 v92, 16, v136
	v_and_b32_e32 v93, 0xffff0000, v136
	v_lshlrev_b32_e32 v94, 16, v137
	v_and_b32_e32 v95, 0xffff0000, v137
	v_cvt_pk_bf16_f32 v90, v90, v91
	v_cvt_pk_bf16_f32 v91, v96, v97
	v_lshlrev_b32_e32 v96, 16, v138
	v_and_b32_e32 v97, 0xffff0000, v138
	v_pk_add_f32 v[86:87], v[86:87], v[94:95]
	v_pk_add_f32 v[84:85], v[84:85], v[92:93]
	v_lshlrev_b32_e32 v98, 16, v139
	v_and_b32_e32 v99, 0xffff0000, v139
	v_pk_add_f32 v[94:95], v[80:81], v[96:97]
	v_mul_f32_e32 v80, v85, v85
	v_mul_f32_e32 v81, v87, v87
	v_pk_add_f32 v[92:93], v[82:83], v[98:99]
	v_fmac_f32_e32 v80, v84, v84
	v_fmac_f32_e32 v81, v86, v86
	v_add_f32_e32 v80, v80, v81
	v_mul_f32_e32 v81, v95, v95
	v_mul_f32_e32 v82, v93, v93
	v_fmac_f32_e32 v81, v94, v94
	v_fmac_f32_e32 v82, v92, v92
	v_add_f32_e32 v81, v81, v82
	v_add_f32_e32 v80, v80, v81
	v_add_f32_e32 v83, v100, v80
	v_mov_b32_e32 v98, v83
	v_lshl_add_u64 v[80:81], s[16:17], 0, v[180:181]
	v_lshl_add_u64 v[96:97], v[168:169], 1, v[80:81]
	global_store_dwordx4 v[96:97], v[88:91], off
	v_cvt_pk_bf16_f32 v82, v84, v85
	s_waitcnt lgkmcnt(0)
	v_permlane16_swap_b32_e32 v83, v98
	v_add_f32_e32 v80, v83, v98
	v_mov_b32_e32 v81, v80
	v_cvt_pk_bf16_f32 v83, v86, v87
	v_cvt_pk_bf16_f32 v84, v94, v95
	v_cvt_pk_bf16_f32 v85, v92, v93
	global_store_dwordx4 v[96:97], v[82:85], off offset:256
	v_permlane32_swap_b32_e32 v80, v81
	v_add_f32_e32 v80, v80, v81
	s_and_saveexec_b64 s[34:35], s[4:5]
	s_cbranch_execz .LBB0_1133
	v_lshlrev_b64 v[82:83], 6, v[178:179]
	v_lshl_add_u64 v[82:83], s[22:23], 0, v[82:83]
	v_lshl_add_u64 v[82:83], s[30:31], 2, v[82:83]
	s_lshl_b32 s10, s45, 2
	v_lshl_add_u64 v[82:83], v[82:83], 0, s[10:11]
	global_store_dword v[82:83], v80, off
.LBB0_1133:
	s_or_b64 exec, exec, s[34:35]
	v_lshlrev_b32_e32 v80, 16, v132
	s_waitcnt lgkmcnt(0)
	v_and_b32_e32 v81, 0xffff0000, v132
	v_lshlrev_b32_e32 v82, 16, v133
	v_and_b32_e32 v83, 0xffff0000, v133
	v_lshlrev_b32_e32 v84, 16, v134
	v_and_b32_e32 v85, 0xffff0000, v134
	v_lshlrev_b32_e32 v86, 16, v135
	v_and_b32_e32 v87, 0xffff0000, v135
	v_pk_add_f32 v[78:79], v[78:79], v[82:83]
	v_pk_add_f32 v[76:77], v[76:77], v[80:81]
	v_pk_add_f32 v[80:81], v[74:75], v[86:87]
	v_pk_add_f32 v[74:75], v[72:73], v[84:85]
	v_mul_f32_e32 v72, v77, v77
	v_mul_f32_e32 v73, v79, v79
	v_fmac_f32_e32 v72, v76, v76
	v_fmac_f32_e32 v73, v78, v78
	v_add_f32_e32 v72, v72, v73
	v_mul_f32_e32 v73, v75, v75
	v_mul_f32_e32 v82, v81, v81
	v_fmac_f32_e32 v73, v74, v74
	v_fmac_f32_e32 v82, v80, v80
	v_add_f32_e32 v73, v73, v82
	v_add_f32_e32 v84, v72, v73
	v_cvt_pk_bf16_f32 v72, v76, v77
	v_cvt_pk_bf16_f32 v73, v78, v79
	v_lshlrev_b32_e32 v76, 16, v128
	v_and_b32_e32 v77, 0xffff0000, v128
	v_lshlrev_b32_e32 v78, 16, v129
	v_and_b32_e32 v79, 0xffff0000, v129
	v_cvt_pk_bf16_f32 v74, v74, v75
	v_cvt_pk_bf16_f32 v75, v80, v81
	v_lshlrev_b32_e32 v80, 16, v130
	v_and_b32_e32 v81, 0xffff0000, v130
	v_pk_add_f32 v[70:71], v[70:71], v[78:79]
	v_pk_add_f32 v[68:69], v[68:69], v[76:77]
	v_lshlrev_b32_e32 v82, 16, v131
	v_and_b32_e32 v83, 0xffff0000, v131
	v_pk_add_f32 v[78:79], v[64:65], v[80:81]
	v_mul_f32_e32 v64, v69, v69
	v_mul_f32_e32 v65, v71, v71
	v_pk_add_f32 v[76:77], v[66:67], v[82:83]
	v_fmac_f32_e32 v64, v68, v68
	v_fmac_f32_e32 v65, v70, v70
	v_add_f32_e32 v64, v64, v65
	v_mul_f32_e32 v65, v79, v79
	v_mul_f32_e32 v66, v77, v77
	v_fmac_f32_e32 v65, v78, v78
	v_fmac_f32_e32 v66, v76, v76
	v_add_f32_e32 v65, v65, v66
	v_add_f32_e32 v64, v64, v65
	v_add_f32_e32 v67, v84, v64
	v_mov_b32_e32 v82, v67
	v_lshl_add_u64 v[64:65], s[16:17], 0, v[176:177]
	v_lshl_add_u64 v[80:81], v[168:169], 1, v[64:65]
	global_store_dwordx4 v[80:81], v[72:75], off
	v_cvt_pk_bf16_f32 v66, v68, v69
	s_waitcnt lgkmcnt(0)
	v_permlane16_swap_b32_e32 v67, v82
	v_add_f32_e32 v64, v67, v82
	v_mov_b32_e32 v65, v64
	v_cvt_pk_bf16_f32 v67, v70, v71
	v_cvt_pk_bf16_f32 v68, v78, v79
	v_cvt_pk_bf16_f32 v69, v76, v77
	global_store_dwordx4 v[80:81], v[66:69], off offset:256
	v_permlane32_swap_b32_e32 v64, v65
	v_add_f32_e32 v64, v64, v65
	s_and_saveexec_b64 s[34:35], s[4:5]
	s_cbranch_execz .LBB0_1135
	v_lshlrev_b64 v[66:67], 6, v[174:175]
	v_lshl_add_u64 v[66:67], s[22:23], 0, v[66:67]
	v_lshl_add_u64 v[66:67], s[30:31], 2, v[66:67]
	s_lshl_b32 s10, s45, 2
	v_lshl_add_u64 v[66:67], v[66:67], 0, s[10:11]
	global_store_dword v[66:67], v64, off
.LBB0_1135:
	s_or_b64 exec, exec, s[34:35]
	v_add_u32_e32 v100, 0x80, v172
	v_ashrrev_i32_e32 v101, 31, v100
	v_lshlrev_b64 v[110:111], 11, v[100:101]
	s_waitcnt lgkmcnt(0)
	v_lshl_add_u64 v[64:65], v[170:171], 0, v[110:111]
	v_add_u32_e32 v96, 0x90, v172
	v_add_u32_e32 v92, 0xa0, v172
	v_add_u32_e32 v88, 0xb0, v172
	v_ashrrev_i32_e32 v97, 31, v96
	v_ashrrev_i32_e32 v93, 31, v92
	v_ashrrev_i32_e32 v89, 31, v88
	v_lshlrev_b64 v[98:99], 11, v[96:97]
	v_lshlrev_b64 v[94:95], 11, v[92:93]
	v_lshlrev_b64 v[90:91], 11, v[88:89]
	v_lshl_add_u64 v[64:65], v[170:171], 0, v[98:99]
	v_lshl_add_u64 v[66:67], v[170:171], 0, v[94:95]
	v_lshl_add_u64 v[112:113], v[170:171], 0, v[90:91]
	s_waitcnt vmcnt(15)
	v_lshlrev_b32_e32 v112, 16, v216
	v_and_b32_e32 v113, 0xffff0000, v216
	v_lshlrev_b32_e32 v102, 16, v217
	v_and_b32_e32 v103, 0xffff0000, v217
	v_lshlrev_b32_e32 v114, 16, v218
	v_and_b32_e32 v115, 0xffff0000, v218
	v_lshlrev_b32_e32 v104, 16, v219
	v_and_b32_e32 v105, 0xffff0000, v219
	s_waitcnt vmcnt(14)
	v_lshlrev_b32_e32 v116, 16, v220
	v_and_b32_e32 v117, 0xffff0000, v220
	v_lshlrev_b32_e32 v106, 16, v221
	v_and_b32_e32 v107, 0xffff0000, v221
	v_lshlrev_b32_e32 v118, 16, v222
	v_and_b32_e32 v119, 0xffff0000, v222
	v_lshlrev_b32_e32 v108, 16, v223
	v_and_b32_e32 v109, 0xffff0000, v223
	v_pk_add_f32 v[62:63], v[62:63], v[102:103]
	v_pk_add_f32 v[60:61], v[60:61], v[112:113]
	v_pk_add_f32 v[58:59], v[58:59], v[104:105]
	v_pk_add_f32 v[56:57], v[56:57], v[114:115]
	v_pk_add_f32 v[54:55], v[54:55], v[106:107]
	v_pk_add_f32 v[52:53], v[52:53], v[116:117]
	v_pk_add_f32 v[102:103], v[50:51], v[108:109]
	v_pk_add_f32 v[104:105], v[48:49], v[118:119]
	v_mul_f32_e32 v106, v61, v61
	v_mul_f32_e32 v107, v63, v63
	v_mul_f32_e32 v108, v57, v57
	v_mul_f32_e32 v109, v59, v59
	v_cvt_pk_bf16_f32 v48, v60, v61
	v_cvt_pk_bf16_f32 v49, v62, v63
	v_cvt_pk_bf16_f32 v50, v56, v57
	v_cvt_pk_bf16_f32 v51, v58, v59
	v_mul_f32_e32 v57, v53, v53
	v_mul_f32_e32 v59, v55, v55
	v_mul_f32_e32 v61, v105, v105
	v_mul_f32_e32 v63, v103, v103
	v_fmac_f32_e32 v106, v60, v60
	v_fmac_f32_e32 v107, v62, v62
	v_fmac_f32_e32 v108, v56, v56
	v_fmac_f32_e32 v109, v58, v58
	v_fmac_f32_e32 v57, v52, v52
	v_fmac_f32_e32 v59, v54, v54
	v_fmac_f32_e32 v61, v104, v104
	v_fmac_f32_e32 v63, v102, v102
	v_add_f32_e32 v56, v106, v107
	v_add_f32_e32 v58, v108, v109
	v_add_f32_e32 v57, v57, v59
	v_add_f32_e32 v59, v61, v63
	v_add_f32_e32 v56, v56, v58
	v_add_f32_e32 v57, v57, v59
	v_add_f32_e32 v58, v56, v57
	v_mov_b32_e32 v59, v58
	v_lshl_add_u64 v[56:57], s[16:17], 0, v[110:111]
	v_lshl_add_u64 v[56:57], v[168:169], 1, v[56:57]
	global_store_dwordx4 v[56:57], v[48:51], off
	s_waitcnt lgkmcnt(0)
	s_nop 0
	v_permlane16_swap_b32_e32 v58, v59
	v_add_f32_e32 v48, v58, v59
	v_mov_b32_e32 v49, v48
	v_cvt_pk_bf16_f32 v50, v52, v53
	v_cvt_pk_bf16_f32 v51, v54, v55
	v_cvt_pk_bf16_f32 v52, v104, v105
	v_cvt_pk_bf16_f32 v53, v102, v103
	global_store_dwordx4 v[56:57], v[50:53], off offset:256
	v_permlane32_swap_b32_e32 v48, v49
	v_add_f32_e32 v48, v48, v49
	s_and_saveexec_b64 s[34:35], s[4:5]
	s_cbranch_execz .LBB0_1137
	v_lshlrev_b64 v[50:51], 6, v[100:101]
	v_lshl_add_u64 v[50:51], s[22:23], 0, v[50:51]
	v_lshl_add_u64 v[50:51], s[30:31], 2, v[50:51]
	s_lshl_b32 s10, s45, 2
	v_lshl_add_u64 v[50:51], v[50:51], 0, s[10:11]
	global_store_dword v[50:51], v48, off
.LBB0_1137:
	s_or_b64 exec, exec, s[34:35]
	s_waitcnt vmcnt(15)
	v_lshlrev_b32_e32 v48, 16, v224
	s_waitcnt lgkmcnt(0)
	v_and_b32_e32 v49, 0xffff0000, v224
	v_lshlrev_b32_e32 v50, 16, v225
	v_and_b32_e32 v51, 0xffff0000, v225
	v_lshlrev_b32_e32 v52, 16, v226
	v_and_b32_e32 v53, 0xffff0000, v226
	v_lshlrev_b32_e32 v54, 16, v227
	v_and_b32_e32 v55, 0xffff0000, v227
	v_pk_add_f32 v[46:47], v[46:47], v[50:51]
	v_pk_add_f32 v[44:45], v[44:45], v[48:49]
	v_pk_add_f32 v[48:49], v[42:43], v[54:55]
	v_pk_add_f32 v[42:43], v[40:41], v[52:53]
	v_mul_f32_e32 v40, v45, v45
	v_mul_f32_e32 v41, v47, v47
	v_fmac_f32_e32 v40, v44, v44
	v_fmac_f32_e32 v41, v46, v46
	v_add_f32_e32 v40, v40, v41
	v_mul_f32_e32 v41, v43, v43
	v_mul_f32_e32 v50, v49, v49
	v_fmac_f32_e32 v41, v42, v42
	v_fmac_f32_e32 v50, v48, v48
	v_add_f32_e32 v41, v41, v50
	v_add_f32_e32 v52, v40, v41
	v_cvt_pk_bf16_f32 v40, v44, v45
	v_cvt_pk_bf16_f32 v41, v46, v47
	s_waitcnt vmcnt(14)
	v_lshlrev_b32_e32 v44, 16, v228
	v_and_b32_e32 v45, 0xffff0000, v228
	v_lshlrev_b32_e32 v46, 16, v229
	v_and_b32_e32 v47, 0xffff0000, v229
	v_cvt_pk_bf16_f32 v42, v42, v43
	v_cvt_pk_bf16_f32 v43, v48, v49
	v_lshlrev_b32_e32 v48, 16, v230
	v_and_b32_e32 v49, 0xffff0000, v230
	v_pk_add_f32 v[38:39], v[38:39], v[46:47]
	v_pk_add_f32 v[36:37], v[36:37], v[44:45]
	v_lshlrev_b32_e32 v50, 16, v231
	v_and_b32_e32 v51, 0xffff0000, v231
	v_pk_add_f32 v[46:47], v[32:33], v[48:49]
	v_mul_f32_e32 v32, v37, v37
	v_mul_f32_e32 v33, v39, v39
	v_pk_add_f32 v[44:45], v[34:35], v[50:51]
	v_fmac_f32_e32 v32, v36, v36
	v_fmac_f32_e32 v33, v38, v38
	v_add_f32_e32 v32, v32, v33
	v_mul_f32_e32 v33, v47, v47
	v_mul_f32_e32 v34, v45, v45
	v_fmac_f32_e32 v33, v46, v46
	v_fmac_f32_e32 v34, v44, v44
	v_add_f32_e32 v33, v33, v34
	v_add_f32_e32 v32, v32, v33
	v_add_f32_e32 v35, v52, v32
	v_mov_b32_e32 v50, v35
	v_lshl_add_u64 v[32:33], s[16:17], 0, v[98:99]
	v_lshl_add_u64 v[48:49], v[168:169], 1, v[32:33]
	global_store_dwordx4 v[48:49], v[40:43], off
	v_cvt_pk_bf16_f32 v34, v36, v37
	s_waitcnt lgkmcnt(0)
	v_permlane16_swap_b32_e32 v35, v50
	v_add_f32_e32 v32, v35, v50
	v_mov_b32_e32 v33, v32
	v_cvt_pk_bf16_f32 v35, v38, v39
	v_cvt_pk_bf16_f32 v36, v46, v47
	v_cvt_pk_bf16_f32 v37, v44, v45
	global_store_dwordx4 v[48:49], v[34:37], off offset:256
	v_permlane32_swap_b32_e32 v32, v33
	v_add_f32_e32 v32, v32, v33
	s_and_saveexec_b64 s[34:35], s[4:5]
	s_cbranch_execz .LBB0_1139
	v_lshlrev_b64 v[34:35], 6, v[96:97]
	v_lshl_add_u64 v[34:35], s[22:23], 0, v[34:35]
	v_lshl_add_u64 v[34:35], s[30:31], 2, v[34:35]
	s_lshl_b32 s10, s45, 2
	v_lshl_add_u64 v[34:35], v[34:35], 0, s[10:11]
	global_store_dword v[34:35], v32, off
.LBB0_1139:
	s_or_b64 exec, exec, s[34:35]
	s_waitcnt vmcnt(15)
	v_lshlrev_b32_e32 v32, 16, v232
	s_waitcnt lgkmcnt(0)
	v_and_b32_e32 v33, 0xffff0000, v232
	v_lshlrev_b32_e32 v34, 16, v233
	v_and_b32_e32 v35, 0xffff0000, v233
	v_lshlrev_b32_e32 v36, 16, v234
	v_and_b32_e32 v37, 0xffff0000, v234
	v_lshlrev_b32_e32 v38, 16, v235
	v_and_b32_e32 v39, 0xffff0000, v235
	v_pk_add_f32 v[30:31], v[30:31], v[34:35]
	v_pk_add_f32 v[28:29], v[28:29], v[32:33]
	v_pk_add_f32 v[32:33], v[26:27], v[38:39]
	v_pk_add_f32 v[26:27], v[24:25], v[36:37]
	v_mul_f32_e32 v24, v29, v29
	v_mul_f32_e32 v25, v31, v31
	v_fmac_f32_e32 v24, v28, v28
	v_fmac_f32_e32 v25, v30, v30
	v_add_f32_e32 v24, v24, v25
	v_mul_f32_e32 v25, v27, v27
	v_mul_f32_e32 v34, v33, v33
	v_fmac_f32_e32 v25, v26, v26
	v_fmac_f32_e32 v34, v32, v32
	v_add_f32_e32 v25, v25, v34
	v_add_f32_e32 v36, v24, v25
	v_cvt_pk_bf16_f32 v24, v28, v29
	v_cvt_pk_bf16_f32 v25, v30, v31
	s_waitcnt vmcnt(14)
	v_lshlrev_b32_e32 v28, 16, v236
	v_and_b32_e32 v29, 0xffff0000, v236
	v_lshlrev_b32_e32 v30, 16, v237
	v_and_b32_e32 v31, 0xffff0000, v237
	v_cvt_pk_bf16_f32 v26, v26, v27
	v_cvt_pk_bf16_f32 v27, v32, v33
	v_lshlrev_b32_e32 v32, 16, v238
	v_and_b32_e32 v33, 0xffff0000, v238
	v_pk_add_f32 v[22:23], v[22:23], v[30:31]
	v_pk_add_f32 v[20:21], v[20:21], v[28:29]
	v_lshlrev_b32_e32 v34, 16, v239
	v_and_b32_e32 v35, 0xffff0000, v239
	v_pk_add_f32 v[30:31], v[16:17], v[32:33]
	v_mul_f32_e32 v16, v21, v21
	v_mul_f32_e32 v17, v23, v23
	v_pk_add_f32 v[28:29], v[18:19], v[34:35]
	v_fmac_f32_e32 v16, v20, v20
	v_fmac_f32_e32 v17, v22, v22
	v_add_f32_e32 v16, v16, v17
	v_mul_f32_e32 v17, v31, v31
	v_mul_f32_e32 v18, v29, v29
	v_fmac_f32_e32 v17, v30, v30
	v_fmac_f32_e32 v18, v28, v28
	v_add_f32_e32 v17, v17, v18
	v_add_f32_e32 v16, v16, v17
	v_add_f32_e32 v19, v36, v16
	v_mov_b32_e32 v34, v19
	v_lshl_add_u64 v[16:17], s[16:17], 0, v[94:95]
	v_lshl_add_u64 v[32:33], v[168:169], 1, v[16:17]
	global_store_dwordx4 v[32:33], v[24:27], off
	v_cvt_pk_bf16_f32 v18, v20, v21
	s_waitcnt lgkmcnt(0)
	v_permlane16_swap_b32_e32 v19, v34
	v_add_f32_e32 v16, v19, v34
	v_mov_b32_e32 v17, v16
	v_cvt_pk_bf16_f32 v19, v22, v23
	v_cvt_pk_bf16_f32 v20, v30, v31
	v_cvt_pk_bf16_f32 v21, v28, v29
	global_store_dwordx4 v[32:33], v[18:21], off offset:256
	v_permlane32_swap_b32_e32 v16, v17
	v_add_f32_e32 v16, v16, v17
	s_and_saveexec_b64 s[34:35], s[4:5]
	s_cbranch_execz .LBB0_1141
	v_lshlrev_b64 v[18:19], 6, v[92:93]
	v_lshl_add_u64 v[18:19], s[22:23], 0, v[18:19]
	v_lshl_add_u64 v[18:19], s[30:31], 2, v[18:19]
	s_lshl_b32 s10, s45, 2
	v_lshl_add_u64 v[18:19], v[18:19], 0, s[10:11]
	global_store_dword v[18:19], v16, off
.LBB0_1141:
	s_or_b64 exec, exec, s[34:35]
	s_waitcnt vmcnt(15)
	v_lshlrev_b32_e32 v16, 16, v240
	s_waitcnt lgkmcnt(0)
	v_and_b32_e32 v17, 0xffff0000, v240
	v_lshlrev_b32_e32 v18, 16, v241
	v_and_b32_e32 v19, 0xffff0000, v241
	v_lshlrev_b32_e32 v20, 16, v242
	v_and_b32_e32 v21, 0xffff0000, v242
	v_lshlrev_b32_e32 v22, 16, v243
	v_and_b32_e32 v23, 0xffff0000, v243
	v_pk_add_f32 v[14:15], v[14:15], v[18:19]
	v_pk_add_f32 v[12:13], v[12:13], v[16:17]
	v_pk_add_f32 v[16:17], v[10:11], v[22:23]
	v_pk_add_f32 v[10:11], v[8:9], v[20:21]
	v_mul_f32_e32 v8, v13, v13
	v_mul_f32_e32 v9, v15, v15
	v_fmac_f32_e32 v8, v12, v12
	v_fmac_f32_e32 v9, v14, v14
	v_add_f32_e32 v8, v8, v9
	v_mul_f32_e32 v9, v11, v11
	v_mul_f32_e32 v18, v17, v17
	v_fmac_f32_e32 v9, v10, v10
	v_fmac_f32_e32 v18, v16, v16
	v_add_f32_e32 v9, v9, v18
	v_add_f32_e32 v20, v8, v9
	v_cvt_pk_bf16_f32 v8, v12, v13
	v_cvt_pk_bf16_f32 v9, v14, v15
	s_waitcnt vmcnt(14)
	v_lshlrev_b32_e32 v12, 16, v244
	v_and_b32_e32 v13, 0xffff0000, v244
	v_lshlrev_b32_e32 v14, 16, v245
	v_and_b32_e32 v15, 0xffff0000, v245
	v_cvt_pk_bf16_f32 v10, v10, v11
	v_cvt_pk_bf16_f32 v11, v16, v17
	v_lshlrev_b32_e32 v16, 16, v246
	v_and_b32_e32 v17, 0xffff0000, v246
	v_pk_add_f32 v[6:7], v[6:7], v[14:15]
	v_pk_add_f32 v[4:5], v[4:5], v[12:13]
	v_lshlrev_b32_e32 v18, 16, v247
	v_and_b32_e32 v19, 0xffff0000, v247
	v_pk_add_f32 v[14:15], v[0:1], v[16:17]
	v_mul_f32_e32 v0, v5, v5
	v_mul_f32_e32 v1, v7, v7
	v_pk_add_f32 v[12:13], v[2:3], v[18:19]
	v_fmac_f32_e32 v0, v4, v4
	v_fmac_f32_e32 v1, v6, v6
	v_add_f32_e32 v0, v0, v1
	v_mul_f32_e32 v1, v15, v15
	v_mul_f32_e32 v2, v13, v13
	v_fmac_f32_e32 v1, v14, v14
	v_fmac_f32_e32 v2, v12, v12
	v_add_f32_e32 v1, v1, v2
	v_add_f32_e32 v0, v0, v1
	v_add_f32_e32 v3, v20, v0
	v_mov_b32_e32 v18, v3
	v_lshl_add_u64 v[0:1], s[16:17], 0, v[90:91]
	v_lshl_add_u64 v[16:17], v[168:169], 1, v[0:1]
	global_store_dwordx4 v[16:17], v[8:11], off
	v_cvt_pk_bf16_f32 v2, v4, v5
	s_waitcnt lgkmcnt(0)
	v_permlane16_swap_b32_e32 v3, v18
	v_add_f32_e32 v0, v3, v18
	v_mov_b32_e32 v1, v0
	v_cvt_pk_bf16_f32 v3, v6, v7
	v_cvt_pk_bf16_f32 v4, v14, v15
	v_cvt_pk_bf16_f32 v5, v12, v13
	global_store_dwordx4 v[16:17], v[2:5], off offset:256
	v_permlane32_swap_b32_e32 v0, v1
	v_add_f32_e32 v0, v0, v1
	s_and_saveexec_b64 s[34:35], s[4:5]
	s_cbranch_execz .LBB0_1143
	v_lshlrev_b64 v[2:3], 6, v[88:89]
	v_lshl_add_u64 v[2:3], s[22:23], 0, v[2:3]
	v_lshl_add_u64 v[2:3], s[30:31], 2, v[2:3]
	s_lshl_b32 s10, s45, 2
	v_lshl_add_u64 v[2:3], v[2:3], 0, s[10:11]
	global_store_dword v[2:3], v0, off
